# k4 plus LN-epilogue cross-row sums via v_permlane16/32_swap instead of ds_bpermute
# speedup vs baseline: 1.0062x; 1.0007x over previous
; __device__ __forceinline__ float bflo(unsigned w) { return __uint_as_float(w << 16); }
; __device__ __forceinline__ float bfhi(unsigned w) { return __uint_as_float(w & 0xffff0000u); }
;     __device__ __forceinline__ void operator()(f32x4 (&acc)[2][2][4][2], const Unit& u, int wr, int wc, int fr, int fq, int wid, int lane) const {
;     ...
;             for (int m = 0; m < 4; ++m) { const size_t off = (size_t)(row0 + ai * HALF + m * 16) * D + col0;
; #pragma unroll
;                 for (int bj = 0; bj < 2; ++bj) { f32x4 x0, x1;
;                     if (X) { x0 = *(const f32x4*)(X + off + bj * HALF); x1 = *(const f32x4*)(X + off + bj * HALF + 4); }
;                     else { const u32x4 xw = *(const u32x4*)(XB + off + bj * HALF); x0 = (f32x4){bflo(xw.x), bfhi(xw.x), bflo(xw.y), bfhi(xw.y)}; x1 = (f32x4){bflo(xw.z), bfhi(xw.z), bflo(xw.w), bfhi(xw.w)}; }
;                     acc[ai][bj][m][0] = x0 * ALPHA + acc[ai][bj][m][0]; acc[ai][bj][m][1] = x1 * ALPHA + acc[ai][bj][m][1]; }
;                 asm volatile("" : "+v"(acc[ai][0][m][0]), "+v"(acc[ai][0][m][1]), "+v"(acc[ai][1][m][0]), "+v"(acc[ai][1][m][1]));
;                 float s = 0.f;
; #pragma unroll
;                 for (int bj = 0; bj < 2; ++bj)
; #pragma unroll
;                     for (int n = 0; n < 2; ++n) { const f32x4 x = acc[ai][bj][m][n]; s += (x[0] + x[1]) + (x[2] + x[3]); }
;                 s += __shfl_xor(s, 16); s += __shfl_xor(s, 32);
;                 const float mw = s * (1.0f / 64.0f); float q = 0.f;
; #pragma unroll
;                 for (int bj = 0; bj < 2; ++bj)
; #pragma unroll
;                     for (int n = 0; n < 2; ++n) { const f32x4 d = acc[ai][bj][m][n] - mw; q += (d[0] * d[0] + d[1] * d[1]) + (d[2] * d[2] + d[3] * d[3]); }
;                 q += __shfl_xor(q, 16); q += __shfl_xor(q, 32);
;                 if (fq == 0) P[(ai * HALF + wr * 64 + m * 16 + fr) * 4 + wc] = (f32x2){mw, q};
.LBB0_676:
	s_waitcnt vmcnt(0)
	v_pk_fma_f32 v[38:39], v[134:135], s[92:93], v[38:39] op_sel_hi:[1,0,1]
	v_pk_fma_f32 v[36:37], v[132:133], s[92:93], v[36:37] op_sel_hi:[1,0,1]
	v_pk_fma_f32 v[42:43], v[138:139], s[92:93], v[42:43] op_sel_hi:[1,0,1]
	v_pk_fma_f32 v[40:41], v[136:137], s[92:93], v[40:41] op_sel_hi:[1,0,1]
	v_pk_fma_f32 v[10:11], v[142:143], s[92:93], v[10:11] op_sel_hi:[1,0,1]
	v_pk_fma_f32 v[8:9], v[140:141], s[92:93], v[8:9] op_sel_hi:[1,0,1]
	v_pk_fma_f32 v[6:7], v[146:147], s[92:93], v[6:7] op_sel_hi:[1,0,1]
	v_pk_fma_f32 v[4:5], v[144:145], s[92:93], v[4:5] op_sel_hi:[1,0,1]
	s_nop 0
	s_nop 0
	v_mov_b32_e32 v132, v37
	v_mov_b32_e32 v133, v38
	v_mov_b32_e32 v134, v36
	v_mov_b32_e32 v135, v39
	v_pk_add_f32 v[132:133], v[132:133], v[134:135]
	v_mov_b32_e32 v134, v41
	v_mov_b32_e32 v135, v42
	v_mov_b32_e32 v136, v40
	v_mov_b32_e32 v137, v43
	v_pk_add_f32 v[134:135], v[134:135], v[136:137]
	v_add_f32_e32 v132, v132, v133
	v_pk_add_f32 v[134:135], v[134:135], v[134:135] op_sel_hi:[0,1]
	v_add_f32_e32 v133, 0, v132
	v_add_f32_e32 v137, v8, v9
	v_add_f32_e32 v139, v10, v11
	v_mov_b32_e32 v136, v4
	v_mov_b32_e32 v138, v5
	v_mov_b32_e32 v134, v6
	v_mov_b32_e32 v132, v7
	v_pk_add_f32 v[136:137], v[136:137], v[138:139]
	v_pk_add_f32 v[132:133], v[134:135], v[132:133]
	v_and_b32_e32 v134, 64, v202
	v_pk_add_f32 v[132:133], v[136:137], v[132:133]
	v_add_u32_e32 v134, 64, v134
	v_add_f32_e32 v132, v132, v133
	v_xor_b32_e32 v133, 16, v202
	v_cmp_lt_i32_e32 vcc, v133, v134
	s_nop 1
	v_cndmask_b32_e32 v133, v202, v133, vcc
	v_lshlrev_b32_e32 v178, 2, v133
	v_mov_b32_e32 v133, v132
	s_nop 1
	v_permlane16_swap_b32_e32 v133, v132
	s_waitcnt lgkmcnt(0)
	v_add_f32_e32 v132, v132, v133
	v_xor_b32_e32 v133, 32, v202
	v_cmp_lt_i32_e32 vcc, v133, v134
	s_nop 1
	v_cndmask_b32_e32 v133, v202, v133, vcc
	v_lshlrev_b32_e32 v179, 2, v133
	v_mov_b32_e32 v133, v132
	s_nop 1
	v_permlane32_swap_b32_e32 v133, v132
	s_waitcnt lgkmcnt(0)
	v_add_f32_e32 v132, v132, v133
	v_fmamk_f32 v134, v132, 0xbc800000, v39
	v_fmamk_f32 v136, v132, 0xbc800000, v37
	v_fmamk_f32 v133, v132, 0xbc800000, v38
	v_fmamk_f32 v135, v132, 0xbc800000, v36
	v_mul_f32_e32 v136, v136, v136
	v_mul_f32_e32 v134, v134, v134
	v_fmac_f32_e32 v136, v135, v135
	v_fmac_f32_e32 v134, v133, v133
	v_fmamk_f32 v135, v132, 0xbc800000, v43
	v_fmamk_f32 v137, v132, 0xbc800000, v41
	v_add_f32_e32 v133, v136, v134
	v_fmamk_f32 v134, v132, 0xbc800000, v42
	v_fmamk_f32 v136, v132, 0xbc800000, v40
	v_mul_f32_e32 v137, v137, v137
	v_mul_f32_e32 v135, v135, v135
	v_fmac_f32_e32 v137, v136, v136
	v_fmac_f32_e32 v135, v134, v134
	v_add_f32_e32 v134, v137, v135
	v_fmamk_f32 v135, v132, 0xbc800000, v11
	v_fmamk_f32 v137, v132, 0xbc800000, v9
	v_add_f32_e32 v133, v133, v134
	v_fmamk_f32 v134, v132, 0xbc800000, v10
	v_fmamk_f32 v136, v132, 0xbc800000, v8
	v_mul_f32_e32 v137, v137, v137
	v_mul_f32_e32 v135, v135, v135
	v_fmac_f32_e32 v137, v136, v136
	v_fmac_f32_e32 v135, v134, v134
	v_add_f32_e32 v134, v137, v135
	v_fmamk_f32 v135, v132, 0xbc800000, v7
	v_fmamk_f32 v137, v132, 0xbc800000, v5
	v_add_f32_e32 v133, v134, v133
	v_fmamk_f32 v134, v132, 0xbc800000, v6
	v_fmamk_f32 v136, v132, 0xbc800000, v4
	v_mul_f32_e32 v137, v137, v137
	v_mul_f32_e32 v135, v135, v135
	v_fmac_f32_e32 v137, v136, v136
	v_fmac_f32_e32 v135, v134, v134
	v_add_f32_e32 v134, v137, v135
	v_add_f32_e32 v133, v134, v133
	v_mov_b32_e32 v134, v133
	s_nop 1
	v_permlane16_swap_b32_e32 v134, v133
	s_waitcnt lgkmcnt(0)
	v_add_f32_e32 v133, v133, v134
	v_mov_b32_e32 v134, v133
	s_nop 1
	v_permlane32_swap_b32_e32 v134, v133
	s_and_saveexec_b64 s[62:63], s[4:5]
	s_cbranch_execz .LBB0_678
	v_mul_f32_e32 v132, 0x3c800000, v132
	s_waitcnt lgkmcnt(0)
	v_add_f32_e32 v133, v133, v134
	ds_write_b64 v206, v[132:133]

; __device__ __forceinline__ float bflo(unsigned w) { return __uint_as_float(w << 16); }
; __device__ __forceinline__ float bfhi(unsigned w) { return __uint_as_float(w & 0xffff0000u); }
;     __device__ __forceinline__ void operator()(f32x4 (&acc)[2][2][4][2], const Unit& u, int wr, int wc, int fr, int fq, int wid, int lane) const {
;     ...
;             for (int m = 0; m < 4; ++m) { const size_t off = (size_t)(row0 + ai * HALF + m * 16) * D + col0;
; #pragma unroll
;                 for (int bj = 0; bj < 2; ++bj) { f32x4 x0, x1;
;                     if (X) { x0 = *(const f32x4*)(X + off + bj * HALF); x1 = *(const f32x4*)(X + off + bj * HALF + 4); }
;                     else { const u32x4 xw = *(const u32x4*)(XB + off + bj * HALF); x0 = (f32x4){bflo(xw.x), bfhi(xw.x), bflo(xw.y), bfhi(xw.y)}; x1 = (f32x4){bflo(xw.z), bfhi(xw.z), bflo(xw.w), bfhi(xw.w)}; }
;                     acc[ai][bj][m][0] = x0 * ALPHA + acc[ai][bj][m][0]; acc[ai][bj][m][1] = x1 * ALPHA + acc[ai][bj][m][1]; }
;                 asm volatile("" : "+v"(acc[ai][0][m][0]), "+v"(acc[ai][0][m][1]), "+v"(acc[ai][1][m][0]), "+v"(acc[ai][1][m][1]));
;                 float s = 0.f;
; #pragma unroll
;                 for (int bj = 0; bj < 2; ++bj)
; #pragma unroll
;                     for (int n = 0; n < 2; ++n) { const f32x4 x = acc[ai][bj][m][n]; s += (x[0] + x[1]) + (x[2] + x[3]); }
;                 s += __shfl_xor(s, 16); s += __shfl_xor(s, 32);
;                 const float mw = s * (1.0f / 64.0f); float q = 0.f;
; #pragma unroll
;                 for (int bj = 0; bj < 2; ++bj)
; #pragma unroll
;                     for (int n = 0; n < 2; ++n) { const f32x4 d = acc[ai][bj][m][n] - mw; q += (d[0] * d[0] + d[1] * d[1]) + (d[2] * d[2] + d[3] * d[3]); }
;                 q += __shfl_xor(q, 16); q += __shfl_xor(q, 32);
;                 if (fq == 0) P[(ai * HALF + wr * 64 + m * 16 + fr) * 4 + wc] = (f32x2){mw, q};
.LBB0_684:
	s_waitcnt vmcnt(0) lgkmcnt(0)
	v_pk_fma_f32 v[70:71], v[134:135], s[92:93], v[70:71] op_sel_hi:[1,0,1]
	v_pk_fma_f32 v[68:69], v[132:133], s[92:93], v[68:69] op_sel_hi:[1,0,1]
	v_pk_fma_f32 v[74:75], v[138:139], s[92:93], v[74:75] op_sel_hi:[1,0,1]
	v_pk_fma_f32 v[72:73], v[136:137], s[92:93], v[72:73] op_sel_hi:[1,0,1]
	v_pk_fma_f32 v[34:35], v[142:143], s[92:93], v[34:35] op_sel_hi:[1,0,1]
	v_pk_fma_f32 v[32:33], v[140:141], s[92:93], v[32:33] op_sel_hi:[1,0,1]
	v_pk_fma_f32 v[30:31], v[146:147], s[92:93], v[30:31] op_sel_hi:[1,0,1]
	v_pk_fma_f32 v[28:29], v[144:145], s[92:93], v[28:29] op_sel_hi:[1,0,1]
	s_nop 0
	s_nop 0
	v_mov_b32_e32 v132, v69
	v_mov_b32_e32 v133, v70
	v_mov_b32_e32 v134, v68
	v_mov_b32_e32 v135, v71
	v_pk_add_f32 v[132:133], v[132:133], v[134:135]
	v_mov_b32_e32 v134, v73
	v_mov_b32_e32 v135, v74
	v_mov_b32_e32 v136, v72
	v_mov_b32_e32 v137, v75
	v_pk_add_f32 v[134:135], v[134:135], v[136:137]
	v_add_f32_e32 v132, v132, v133
	v_pk_add_f32 v[134:135], v[134:135], v[134:135] op_sel_hi:[0,1]
	v_add_f32_e32 v133, 0, v132
	v_add_f32_e32 v137, v32, v33
	v_add_f32_e32 v139, v34, v35
	v_mov_b32_e32 v136, v28
	v_mov_b32_e32 v138, v29
	v_mov_b32_e32 v134, v30
	v_mov_b32_e32 v132, v31
	v_pk_add_f32 v[136:137], v[136:137], v[138:139]
	v_pk_add_f32 v[132:133], v[134:135], v[132:133]
	s_nop 0
	v_pk_add_f32 v[132:133], v[136:137], v[132:133]
	s_nop 0
	v_add_f32_e32 v132, v132, v133
	v_mov_b32_e32 v133, v132
	s_nop 1
	v_permlane16_swap_b32_e32 v133, v132
	s_waitcnt lgkmcnt(0)
	v_add_f32_e32 v132, v132, v133
	v_mov_b32_e32 v133, v132
	s_nop 1
	v_permlane32_swap_b32_e32 v133, v132
	s_waitcnt lgkmcnt(0)
	v_add_f32_e32 v132, v132, v133
	v_fmamk_f32 v134, v132, 0xbc800000, v71
	v_fmamk_f32 v136, v132, 0xbc800000, v69
	v_fmamk_f32 v133, v132, 0xbc800000, v70
	v_fmamk_f32 v135, v132, 0xbc800000, v68
	v_mul_f32_e32 v136, v136, v136
	v_mul_f32_e32 v134, v134, v134
	v_fmac_f32_e32 v136, v135, v135
	v_fmac_f32_e32 v134, v133, v133
	v_fmamk_f32 v135, v132, 0xbc800000, v75
	v_fmamk_f32 v137, v132, 0xbc800000, v73
	v_add_f32_e32 v133, v136, v134
	v_fmamk_f32 v134, v132, 0xbc800000, v74
	v_fmamk_f32 v136, v132, 0xbc800000, v72
	v_mul_f32_e32 v137, v137, v137
	v_mul_f32_e32 v135, v135, v135
	v_fmac_f32_e32 v137, v136, v136
	v_fmac_f32_e32 v135, v134, v134
	v_add_f32_e32 v134, v137, v135
	v_fmamk_f32 v135, v132, 0xbc800000, v35
	v_fmamk_f32 v137, v132, 0xbc800000, v33
	v_add_f32_e32 v133, v133, v134
	v_fmamk_f32 v134, v132, 0xbc800000, v34
	v_fmamk_f32 v136, v132, 0xbc800000, v32
	v_mul_f32_e32 v137, v137, v137
	v_mul_f32_e32 v135, v135, v135
	v_fmac_f32_e32 v137, v136, v136
	v_fmac_f32_e32 v135, v134, v134
	v_add_f32_e32 v134, v137, v135
	v_fmamk_f32 v135, v132, 0xbc800000, v31
	v_fmamk_f32 v137, v132, 0xbc800000, v29
	v_add_f32_e32 v133, v134, v133
	v_fmamk_f32 v134, v132, 0xbc800000, v30
	v_fmamk_f32 v136, v132, 0xbc800000, v28
	v_mul_f32_e32 v137, v137, v137
	v_mul_f32_e32 v135, v135, v135
	v_fmac_f32_e32 v137, v136, v136
	v_fmac_f32_e32 v135, v134, v134
	v_add_f32_e32 v134, v137, v135
	v_add_f32_e32 v133, v134, v133
	v_mov_b32_e32 v134, v133
	s_nop 1
	v_permlane16_swap_b32_e32 v134, v133
	s_waitcnt lgkmcnt(0)
	v_add_f32_e32 v133, v133, v134
	v_mov_b32_e32 v134, v133
	s_nop 1
	v_permlane32_swap_b32_e32 v134, v133
	s_and_saveexec_b64 s[62:63], s[4:5]
	s_cbranch_execz .LBB0_686
	v_mul_f32_e32 v132, 0x3c800000, v132
	s_waitcnt lgkmcnt(0)
	v_add_f32_e32 v133, v133, v134
	ds_write_b64 v206, v[132:133] offset:512

; __device__ __forceinline__ float bflo(unsigned w) { return __uint_as_float(w << 16); }
; __device__ __forceinline__ float bfhi(unsigned w) { return __uint_as_float(w & 0xffff0000u); }
;     __device__ __forceinline__ void operator()(f32x4 (&acc)[2][2][4][2], const Unit& u, int wr, int wc, int fr, int fq, int wid, int lane) const {
;     ...
;             for (int m = 0; m < 4; ++m) { const size_t off = (size_t)(row0 + ai * HALF + m * 16) * D + col0;
; #pragma unroll
;                 for (int bj = 0; bj < 2; ++bj) { f32x4 x0, x1;
;                     if (X) { x0 = *(const f32x4*)(X + off + bj * HALF); x1 = *(const f32x4*)(X + off + bj * HALF + 4); }
;                     else { const u32x4 xw = *(const u32x4*)(XB + off + bj * HALF); x0 = (f32x4){bflo(xw.x), bfhi(xw.x), bflo(xw.y), bfhi(xw.y)}; x1 = (f32x4){bflo(xw.z), bfhi(xw.z), bflo(xw.w), bfhi(xw.w)}; }
;                     acc[ai][bj][m][0] = x0 * ALPHA + acc[ai][bj][m][0]; acc[ai][bj][m][1] = x1 * ALPHA + acc[ai][bj][m][1]; }
;                 asm volatile("" : "+v"(acc[ai][0][m][0]), "+v"(acc[ai][0][m][1]), "+v"(acc[ai][1][m][0]), "+v"(acc[ai][1][m][1]));
;                 float s = 0.f;
; #pragma unroll
;                 for (int bj = 0; bj < 2; ++bj)
; #pragma unroll
;                     for (int n = 0; n < 2; ++n) { const f32x4 x = acc[ai][bj][m][n]; s += (x[0] + x[1]) + (x[2] + x[3]); }
;                 s += __shfl_xor(s, 16); s += __shfl_xor(s, 32);
;                 const float mw = s * (1.0f / 64.0f); float q = 0.f;
; #pragma unroll
;                 for (int bj = 0; bj < 2; ++bj)
; #pragma unroll
;                     for (int n = 0; n < 2; ++n) { const f32x4 d = acc[ai][bj][m][n] - mw; q += (d[0] * d[0] + d[1] * d[1]) + (d[2] * d[2] + d[3] * d[3]); }
;                 q += __shfl_xor(q, 16); q += __shfl_xor(q, 32);
;                 if (fq == 0) P[(ai * HALF + wr * 64 + m * 16 + fr) * 4 + wc] = (f32x2){mw, q};
.LBB0_692:
	s_waitcnt vmcnt(0) lgkmcnt(0)
	v_pk_fma_f32 v[102:103], v[134:135], s[92:93], v[102:103] op_sel_hi:[1,0,1]
	v_pk_fma_f32 v[100:101], v[132:133], s[92:93], v[100:101] op_sel_hi:[1,0,1]
	v_pk_fma_f32 v[106:107], v[138:139], s[92:93], v[106:107] op_sel_hi:[1,0,1]
	v_pk_fma_f32 v[104:105], v[136:137], s[92:93], v[104:105] op_sel_hi:[1,0,1]
	v_pk_fma_f32 v[58:59], v[142:143], s[92:93], v[58:59] op_sel_hi:[1,0,1]
	v_pk_fma_f32 v[56:57], v[140:141], s[92:93], v[56:57] op_sel_hi:[1,0,1]
	v_pk_fma_f32 v[54:55], v[146:147], s[92:93], v[54:55] op_sel_hi:[1,0,1]
	v_pk_fma_f32 v[52:53], v[144:145], s[92:93], v[52:53] op_sel_hi:[1,0,1]
	s_nop 0
	s_nop 0
	v_mov_b32_e32 v132, v101
	v_mov_b32_e32 v133, v102
	v_mov_b32_e32 v134, v100
	v_mov_b32_e32 v135, v103
	v_pk_add_f32 v[132:133], v[132:133], v[134:135]
	v_mov_b32_e32 v134, v105
	v_mov_b32_e32 v135, v106
	v_mov_b32_e32 v136, v104
	v_mov_b32_e32 v137, v107
	v_pk_add_f32 v[134:135], v[134:135], v[136:137]
	v_add_f32_e32 v132, v132, v133
	v_pk_add_f32 v[134:135], v[134:135], v[134:135] op_sel_hi:[0,1]
	v_add_f32_e32 v133, 0, v132
	v_add_f32_e32 v137, v56, v57
	v_add_f32_e32 v139, v58, v59
	v_mov_b32_e32 v136, v52
	v_mov_b32_e32 v138, v53
	v_mov_b32_e32 v134, v54
	v_mov_b32_e32 v132, v55
	v_pk_add_f32 v[136:137], v[136:137], v[138:139]
	v_pk_add_f32 v[132:133], v[134:135], v[132:133]
	s_nop 0
	v_pk_add_f32 v[132:133], v[136:137], v[132:133]
	s_nop 0
	v_add_f32_e32 v132, v132, v133
	v_mov_b32_e32 v133, v132
	s_nop 1
	v_permlane16_swap_b32_e32 v133, v132
	s_waitcnt lgkmcnt(0)
	v_add_f32_e32 v132, v132, v133
	v_mov_b32_e32 v133, v132
	s_nop 1
	v_permlane32_swap_b32_e32 v133, v132
	s_waitcnt lgkmcnt(0)
	v_add_f32_e32 v132, v132, v133
	v_fmamk_f32 v134, v132, 0xbc800000, v103
	v_fmamk_f32 v136, v132, 0xbc800000, v101
	v_fmamk_f32 v133, v132, 0xbc800000, v102
	v_fmamk_f32 v135, v132, 0xbc800000, v100
	v_mul_f32_e32 v136, v136, v136
	v_mul_f32_e32 v134, v134, v134
	v_fmac_f32_e32 v136, v135, v135
	v_fmac_f32_e32 v134, v133, v133
	v_fmamk_f32 v135, v132, 0xbc800000, v107
	v_fmamk_f32 v137, v132, 0xbc800000, v105
	v_add_f32_e32 v133, v136, v134
	v_fmamk_f32 v134, v132, 0xbc800000, v106
	v_fmamk_f32 v136, v132, 0xbc800000, v104
	v_mul_f32_e32 v137, v137, v137
	v_mul_f32_e32 v135, v135, v135
	v_fmac_f32_e32 v137, v136, v136
	v_fmac_f32_e32 v135, v134, v134
	v_add_f32_e32 v134, v137, v135
	v_fmamk_f32 v135, v132, 0xbc800000, v59
	v_fmamk_f32 v137, v132, 0xbc800000, v57
	v_add_f32_e32 v133, v133, v134
	v_fmamk_f32 v134, v132, 0xbc800000, v58
	v_fmamk_f32 v136, v132, 0xbc800000, v56
	v_mul_f32_e32 v137, v137, v137
	v_mul_f32_e32 v135, v135, v135
	v_fmac_f32_e32 v137, v136, v136
	v_fmac_f32_e32 v135, v134, v134
	v_add_f32_e32 v134, v137, v135
	v_fmamk_f32 v135, v132, 0xbc800000, v55
	v_fmamk_f32 v137, v132, 0xbc800000, v53
	v_add_f32_e32 v133, v134, v133
	v_fmamk_f32 v134, v132, 0xbc800000, v54
	v_fmamk_f32 v136, v132, 0xbc800000, v52
	v_mul_f32_e32 v137, v137, v137
	v_mul_f32_e32 v135, v135, v135
	v_fmac_f32_e32 v137, v136, v136
	v_fmac_f32_e32 v135, v134, v134
	v_add_f32_e32 v134, v137, v135
	v_add_f32_e32 v133, v134, v133
	v_mov_b32_e32 v134, v133
	s_nop 1
	v_permlane16_swap_b32_e32 v134, v133
	s_waitcnt lgkmcnt(0)
	v_add_f32_e32 v133, v133, v134
	v_mov_b32_e32 v134, v133
	s_nop 1
	v_permlane32_swap_b32_e32 v134, v133
	s_and_saveexec_b64 s[62:63], s[4:5]
	s_cbranch_execz .LBB0_694
	v_mul_f32_e32 v132, 0x3c800000, v132
	s_waitcnt lgkmcnt(0)
	v_add_f32_e32 v133, v133, v134
	ds_write_b64 v206, v[132:133] offset:1024

; __device__ __forceinline__ float bflo(unsigned w) { return __uint_as_float(w << 16); }
; __device__ __forceinline__ float bfhi(unsigned w) { return __uint_as_float(w & 0xffff0000u); }
;     __device__ __forceinline__ void operator()(f32x4 (&acc)[2][2][4][2], const Unit& u, int wr, int wc, int fr, int fq, int wid, int lane) const {
;     ...
;             for (int m = 0; m < 4; ++m) { const size_t off = (size_t)(row0 + ai * HALF + m * 16) * D + col0;
; #pragma unroll
;                 for (int bj = 0; bj < 2; ++bj) { f32x4 x0, x1;
;                     if (X) { x0 = *(const f32x4*)(X + off + bj * HALF); x1 = *(const f32x4*)(X + off + bj * HALF + 4); }
;                     else { const u32x4 xw = *(const u32x4*)(XB + off + bj * HALF); x0 = (f32x4){bflo(xw.x), bfhi(xw.x), bflo(xw.y), bfhi(xw.y)}; x1 = (f32x4){bflo(xw.z), bfhi(xw.z), bflo(xw.w), bfhi(xw.w)}; }
;                     acc[ai][bj][m][0] = x0 * ALPHA + acc[ai][bj][m][0]; acc[ai][bj][m][1] = x1 * ALPHA + acc[ai][bj][m][1]; }
;                 asm volatile("" : "+v"(acc[ai][0][m][0]), "+v"(acc[ai][0][m][1]), "+v"(acc[ai][1][m][0]), "+v"(acc[ai][1][m][1]));
;                 float s = 0.f;
; #pragma unroll
;                 for (int bj = 0; bj < 2; ++bj)
; #pragma unroll
;                     for (int n = 0; n < 2; ++n) { const f32x4 x = acc[ai][bj][m][n]; s += (x[0] + x[1]) + (x[2] + x[3]); }
;                 s += __shfl_xor(s, 16); s += __shfl_xor(s, 32);
;                 const float mw = s * (1.0f / 64.0f); float q = 0.f;
; #pragma unroll
;                 for (int bj = 0; bj < 2; ++bj)
; #pragma unroll
;                     for (int n = 0; n < 2; ++n) { const f32x4 d = acc[ai][bj][m][n] - mw; q += (d[0] * d[0] + d[1] * d[1]) + (d[2] * d[2] + d[3] * d[3]); }
;                 q += __shfl_xor(q, 16); q += __shfl_xor(q, 32);
;                 if (fq == 0) P[(ai * HALF + wr * 64 + m * 16 + fr) * 4 + wc] = (f32x2){mw, q};
.LBB0_700:
	s_waitcnt vmcnt(0) lgkmcnt(0)
	v_pk_fma_f32 v[130:131], v[134:135], s[92:93], v[130:131] op_sel_hi:[1,0,1]
	v_pk_fma_f32 v[128:129], v[132:133], s[92:93], v[128:129] op_sel_hi:[1,0,1]
	v_pk_fma_f32 v[126:127], v[138:139], s[92:93], v[126:127] op_sel_hi:[1,0,1]
	v_pk_fma_f32 v[124:125], v[136:137], s[92:93], v[124:125] op_sel_hi:[1,0,1]
	v_pk_fma_f32 v[82:83], v[142:143], s[92:93], v[82:83] op_sel_hi:[1,0,1]
	v_pk_fma_f32 v[80:81], v[140:141], s[92:93], v[80:81] op_sel_hi:[1,0,1]
	v_pk_fma_f32 v[78:79], v[146:147], s[92:93], v[78:79] op_sel_hi:[1,0,1]
	v_pk_fma_f32 v[76:77], v[144:145], s[92:93], v[76:77] op_sel_hi:[1,0,1]
	s_nop 0
	s_nop 0
	v_mov_b32_e32 v132, v129
	v_mov_b32_e32 v133, v130
	v_mov_b32_e32 v134, v128
	v_mov_b32_e32 v135, v131
	v_pk_add_f32 v[132:133], v[132:133], v[134:135]
	v_mov_b32_e32 v134, v125
	v_mov_b32_e32 v135, v126
	v_mov_b32_e32 v136, v124
	v_mov_b32_e32 v137, v127
	v_pk_add_f32 v[134:135], v[134:135], v[136:137]
	v_add_f32_e32 v132, v132, v133
	v_pk_add_f32 v[134:135], v[134:135], v[134:135] op_sel_hi:[0,1]
	v_add_f32_e32 v133, 0, v132
	v_add_f32_e32 v137, v80, v81
	v_add_f32_e32 v139, v82, v83
	v_mov_b32_e32 v136, v76
	v_mov_b32_e32 v138, v77
	v_mov_b32_e32 v134, v78
	v_mov_b32_e32 v132, v79
	v_pk_add_f32 v[136:137], v[136:137], v[138:139]
	v_pk_add_f32 v[132:133], v[134:135], v[132:133]
	s_nop 0
	v_pk_add_f32 v[132:133], v[136:137], v[132:133]
	s_nop 0
	v_add_f32_e32 v132, v132, v133
	v_mov_b32_e32 v133, v132
	s_nop 1
	v_permlane16_swap_b32_e32 v133, v132
	s_waitcnt lgkmcnt(0)
	v_add_f32_e32 v132, v132, v133
	v_mov_b32_e32 v133, v132
	s_nop 1
	v_permlane32_swap_b32_e32 v133, v132
	s_waitcnt lgkmcnt(0)
	v_add_f32_e32 v132, v132, v133
	v_fmamk_f32 v134, v132, 0xbc800000, v131
	v_fmamk_f32 v136, v132, 0xbc800000, v129
	v_fmamk_f32 v133, v132, 0xbc800000, v130
	v_fmamk_f32 v135, v132, 0xbc800000, v128
	v_mul_f32_e32 v136, v136, v136
	v_mul_f32_e32 v134, v134, v134
	v_fmac_f32_e32 v136, v135, v135
	v_fmac_f32_e32 v134, v133, v133
	v_fmamk_f32 v135, v132, 0xbc800000, v127
	v_fmamk_f32 v137, v132, 0xbc800000, v125
	v_add_f32_e32 v133, v136, v134
	v_fmamk_f32 v134, v132, 0xbc800000, v126
	v_fmamk_f32 v136, v132, 0xbc800000, v124
	v_mul_f32_e32 v137, v137, v137
	v_mul_f32_e32 v135, v135, v135
	v_fmac_f32_e32 v137, v136, v136
	v_fmac_f32_e32 v135, v134, v134
	v_add_f32_e32 v134, v137, v135
	v_fmamk_f32 v135, v132, 0xbc800000, v83
	v_fmamk_f32 v137, v132, 0xbc800000, v81
	v_add_f32_e32 v133, v133, v134
	v_fmamk_f32 v134, v132, 0xbc800000, v82
	v_fmamk_f32 v136, v132, 0xbc800000, v80
	v_mul_f32_e32 v137, v137, v137
	v_mul_f32_e32 v135, v135, v135
	v_fmac_f32_e32 v137, v136, v136
	v_fmac_f32_e32 v135, v134, v134
	v_add_f32_e32 v134, v137, v135
	v_fmamk_f32 v135, v132, 0xbc800000, v79
	v_fmamk_f32 v137, v132, 0xbc800000, v77
	v_add_f32_e32 v133, v134, v133
	v_fmamk_f32 v134, v132, 0xbc800000, v78
	v_fmamk_f32 v136, v132, 0xbc800000, v76
	v_mul_f32_e32 v137, v137, v137
	v_mul_f32_e32 v135, v135, v135
	v_fmac_f32_e32 v137, v136, v136
	v_fmac_f32_e32 v135, v134, v134
	v_add_f32_e32 v134, v137, v135
	v_add_f32_e32 v133, v134, v133
	v_mov_b32_e32 v134, v133
	s_nop 1
	v_permlane16_swap_b32_e32 v134, v133
	s_waitcnt lgkmcnt(0)
	v_add_f32_e32 v133, v133, v134
	v_mov_b32_e32 v134, v133
	s_nop 1
	v_permlane32_swap_b32_e32 v134, v133
	s_and_saveexec_b64 s[62:63], s[4:5]
	s_cbranch_execz .LBB0_702
	v_mul_f32_e32 v132, 0x3c800000, v132
	s_waitcnt lgkmcnt(0)
	v_add_f32_e32 v133, v133, v134
	ds_write_b64 v206, v[132:133] offset:1536

; __device__ __forceinline__ float bflo(unsigned w) { return __uint_as_float(w << 16); }
; __device__ __forceinline__ float bfhi(unsigned w) { return __uint_as_float(w & 0xffff0000u); }
;     __device__ __forceinline__ void operator()(f32x4 (&acc)[2][2][4][2], const Unit& u, int wr, int wc, int fr, int fq, int wid, int lane) const {
;     ...
;             for (int m = 0; m < 4; ++m) { const size_t off = (size_t)(row0 + ai * HALF + m * 16) * D + col0;
; #pragma unroll
;                 for (int bj = 0; bj < 2; ++bj) { f32x4 x0, x1;
;                     if (X) { x0 = *(const f32x4*)(X + off + bj * HALF); x1 = *(const f32x4*)(X + off + bj * HALF + 4); }
;                     else { const u32x4 xw = *(const u32x4*)(XB + off + bj * HALF); x0 = (f32x4){bflo(xw.x), bfhi(xw.x), bflo(xw.y), bfhi(xw.y)}; x1 = (f32x4){bflo(xw.z), bfhi(xw.z), bflo(xw.w), bfhi(xw.w)}; }
;                     acc[ai][bj][m][0] = x0 * ALPHA + acc[ai][bj][m][0]; acc[ai][bj][m][1] = x1 * ALPHA + acc[ai][bj][m][1]; }
;                 asm volatile("" : "+v"(acc[ai][0][m][0]), "+v"(acc[ai][0][m][1]), "+v"(acc[ai][1][m][0]), "+v"(acc[ai][1][m][1]));
;                 float s = 0.f;
; #pragma unroll
;                 for (int bj = 0; bj < 2; ++bj)
; #pragma unroll
;                     for (int n = 0; n < 2; ++n) { const f32x4 x = acc[ai][bj][m][n]; s += (x[0] + x[1]) + (x[2] + x[3]); }
;                 s += __shfl_xor(s, 16); s += __shfl_xor(s, 32);
;                 const float mw = s * (1.0f / 64.0f); float q = 0.f;
; #pragma unroll
;                 for (int bj = 0; bj < 2; ++bj)
; #pragma unroll
;                     for (int n = 0; n < 2; ++n) { const f32x4 d = acc[ai][bj][m][n] - mw; q += (d[0] * d[0] + d[1] * d[1]) + (d[2] * d[2] + d[3] * d[3]); }
;                 q += __shfl_xor(q, 16); q += __shfl_xor(q, 32);
;                 if (fq == 0) P[(ai * HALF + wr * 64 + m * 16 + fr) * 4 + wc] = (f32x2){mw, q};
.LBB0_708:
	s_waitcnt vmcnt(0) lgkmcnt(0)
	v_pk_fma_f32 v[122:123], v[134:135], s[92:93], v[122:123] op_sel_hi:[1,0,1]
	v_pk_fma_f32 v[120:121], v[132:133], s[92:93], v[120:121] op_sel_hi:[1,0,1]
	v_pk_fma_f32 v[118:119], v[138:139], s[92:93], v[118:119] op_sel_hi:[1,0,1]
	v_pk_fma_f32 v[116:117], v[136:137], s[92:93], v[116:117] op_sel_hi:[1,0,1]
	v_pk_fma_f32 v[114:115], v[142:143], s[92:93], v[114:115] op_sel_hi:[1,0,1]
	v_pk_fma_f32 v[112:113], v[140:141], s[92:93], v[112:113] op_sel_hi:[1,0,1]
	v_pk_fma_f32 v[110:111], v[146:147], s[92:93], v[110:111] op_sel_hi:[1,0,1]
	v_pk_fma_f32 v[108:109], v[144:145], s[92:93], v[108:109] op_sel_hi:[1,0,1]
	s_nop 0
	s_nop 0
	v_mov_b32_e32 v132, v121
	v_mov_b32_e32 v133, v122
	v_mov_b32_e32 v134, v120
	v_mov_b32_e32 v135, v123
	v_pk_add_f32 v[132:133], v[132:133], v[134:135]
	v_mov_b32_e32 v134, v117
	v_mov_b32_e32 v135, v118
	v_mov_b32_e32 v136, v116
	v_mov_b32_e32 v137, v119
	v_pk_add_f32 v[134:135], v[134:135], v[136:137]
	v_add_f32_e32 v132, v132, v133
	v_pk_add_f32 v[134:135], v[134:135], v[134:135] op_sel_hi:[0,1]
	v_add_f32_e32 v133, 0, v132
	v_add_f32_e32 v137, v112, v113
	v_add_f32_e32 v139, v114, v115
	v_mov_b32_e32 v136, v108
	v_mov_b32_e32 v138, v109
	v_mov_b32_e32 v134, v110
	v_mov_b32_e32 v132, v111
	v_pk_add_f32 v[136:137], v[136:137], v[138:139]
	v_pk_add_f32 v[132:133], v[134:135], v[132:133]
	s_nop 0
	v_pk_add_f32 v[132:133], v[136:137], v[132:133]
	s_nop 0
	v_add_f32_e32 v132, v132, v133
	v_mov_b32_e32 v133, v132
	s_nop 1
	v_permlane16_swap_b32_e32 v133, v132
	s_waitcnt lgkmcnt(0)
	v_add_f32_e32 v132, v132, v133
	v_mov_b32_e32 v133, v132
	s_nop 1
	v_permlane32_swap_b32_e32 v133, v132
	s_waitcnt lgkmcnt(0)
	v_add_f32_e32 v132, v132, v133
	v_fmamk_f32 v134, v132, 0xbc800000, v123
	v_fmamk_f32 v136, v132, 0xbc800000, v121
	v_fmamk_f32 v133, v132, 0xbc800000, v122
	v_fmamk_f32 v135, v132, 0xbc800000, v120
	v_mul_f32_e32 v136, v136, v136
	v_mul_f32_e32 v134, v134, v134
	v_fmac_f32_e32 v136, v135, v135
	v_fmac_f32_e32 v134, v133, v133
	v_fmamk_f32 v135, v132, 0xbc800000, v119
	v_fmamk_f32 v137, v132, 0xbc800000, v117
	v_add_f32_e32 v133, v136, v134
	v_fmamk_f32 v134, v132, 0xbc800000, v118
	v_fmamk_f32 v136, v132, 0xbc800000, v116
	v_mul_f32_e32 v137, v137, v137
	v_mul_f32_e32 v135, v135, v135
	v_fmac_f32_e32 v137, v136, v136
	v_fmac_f32_e32 v135, v134, v134
	v_add_f32_e32 v134, v137, v135
	v_fmamk_f32 v135, v132, 0xbc800000, v115
	v_fmamk_f32 v137, v132, 0xbc800000, v113
	v_add_f32_e32 v133, v133, v134
	v_fmamk_f32 v134, v132, 0xbc800000, v114
	v_fmamk_f32 v136, v132, 0xbc800000, v112
	v_mul_f32_e32 v137, v137, v137
	v_mul_f32_e32 v135, v135, v135
	v_fmac_f32_e32 v137, v136, v136
	v_fmac_f32_e32 v135, v134, v134
	v_add_f32_e32 v134, v137, v135
	v_fmamk_f32 v135, v132, 0xbc800000, v111
	v_fmamk_f32 v137, v132, 0xbc800000, v109
	v_add_f32_e32 v133, v134, v133
	v_fmamk_f32 v134, v132, 0xbc800000, v110
	v_fmamk_f32 v136, v132, 0xbc800000, v108
	v_mul_f32_e32 v137, v137, v137
	v_mul_f32_e32 v135, v135, v135
	v_fmac_f32_e32 v137, v136, v136
	v_fmac_f32_e32 v135, v134, v134
	v_add_f32_e32 v134, v137, v135
	v_add_f32_e32 v133, v134, v133
	v_mov_b32_e32 v134, v133
	s_nop 1
	v_permlane16_swap_b32_e32 v134, v133
	s_waitcnt lgkmcnt(0)
	v_add_f32_e32 v133, v133, v134
	v_mov_b32_e32 v134, v133
	s_nop 1
	v_permlane32_swap_b32_e32 v134, v133
	s_and_saveexec_b64 s[62:63], s[4:5]
	s_cbranch_execz .LBB0_710
	v_mul_f32_e32 v132, 0x3c800000, v132
	s_waitcnt lgkmcnt(0)
	v_add_f32_e32 v133, v133, v134
	ds_write_b64 v204, v[132:133]

; __device__ __forceinline__ float bflo(unsigned w) { return __uint_as_float(w << 16); }
; __device__ __forceinline__ float bfhi(unsigned w) { return __uint_as_float(w & 0xffff0000u); }
;     __device__ __forceinline__ void operator()(f32x4 (&acc)[2][2][4][2], const Unit& u, int wr, int wc, int fr, int fq, int wid, int lane) const {
;     ...
;             for (int m = 0; m < 4; ++m) { const size_t off = (size_t)(row0 + ai * HALF + m * 16) * D + col0;
; #pragma unroll
;                 for (int bj = 0; bj < 2; ++bj) { f32x4 x0, x1;
;                     if (X) { x0 = *(const f32x4*)(X + off + bj * HALF); x1 = *(const f32x4*)(X + off + bj * HALF + 4); }
;                     else { const u32x4 xw = *(const u32x4*)(XB + off + bj * HALF); x0 = (f32x4){bflo(xw.x), bfhi(xw.x), bflo(xw.y), bfhi(xw.y)}; x1 = (f32x4){bflo(xw.z), bfhi(xw.z), bflo(xw.w), bfhi(xw.w)}; }
;                     acc[ai][bj][m][0] = x0 * ALPHA + acc[ai][bj][m][0]; acc[ai][bj][m][1] = x1 * ALPHA + acc[ai][bj][m][1]; }
;                 asm volatile("" : "+v"(acc[ai][0][m][0]), "+v"(acc[ai][0][m][1]), "+v"(acc[ai][1][m][0]), "+v"(acc[ai][1][m][1]));
;                 float s = 0.f;
; #pragma unroll
;                 for (int bj = 0; bj < 2; ++bj)
; #pragma unroll
;                     for (int n = 0; n < 2; ++n) { const f32x4 x = acc[ai][bj][m][n]; s += (x[0] + x[1]) + (x[2] + x[3]); }
;                 s += __shfl_xor(s, 16); s += __shfl_xor(s, 32);
;                 const float mw = s * (1.0f / 64.0f); float q = 0.f;
; #pragma unroll
;                 for (int bj = 0; bj < 2; ++bj)
; #pragma unroll
;                     for (int n = 0; n < 2; ++n) { const f32x4 d = acc[ai][bj][m][n] - mw; q += (d[0] * d[0] + d[1] * d[1]) + (d[2] * d[2] + d[3] * d[3]); }
;                 q += __shfl_xor(q, 16); q += __shfl_xor(q, 32);
;                 if (fq == 0) P[(ai * HALF + wr * 64 + m * 16 + fr) * 4 + wc] = (f32x2){mw, q};
.LBB0_716:
	s_waitcnt vmcnt(0) lgkmcnt(0)
	v_pk_fma_f32 v[98:99], v[134:135], s[92:93], v[98:99] op_sel_hi:[1,0,1]
	v_pk_fma_f32 v[96:97], v[132:133], s[92:93], v[96:97] op_sel_hi:[1,0,1]
	v_pk_fma_f32 v[94:95], v[138:139], s[92:93], v[94:95] op_sel_hi:[1,0,1]
	v_pk_fma_f32 v[92:93], v[136:137], s[92:93], v[92:93] op_sel_hi:[1,0,1]
	v_pk_fma_f32 v[90:91], v[142:143], s[92:93], v[90:91] op_sel_hi:[1,0,1]
	v_pk_fma_f32 v[88:89], v[140:141], s[92:93], v[88:89] op_sel_hi:[1,0,1]
	v_pk_fma_f32 v[86:87], v[146:147], s[92:93], v[86:87] op_sel_hi:[1,0,1]
	v_pk_fma_f32 v[84:85], v[144:145], s[92:93], v[84:85] op_sel_hi:[1,0,1]
	s_nop 0
	s_nop 0
	v_mov_b32_e32 v132, v97
	v_mov_b32_e32 v133, v98
	v_mov_b32_e32 v134, v96
	v_mov_b32_e32 v135, v99
	v_pk_add_f32 v[132:133], v[132:133], v[134:135]
	v_mov_b32_e32 v134, v93
	v_mov_b32_e32 v135, v94
	v_mov_b32_e32 v136, v92
	v_mov_b32_e32 v137, v95
	v_pk_add_f32 v[134:135], v[134:135], v[136:137]
	v_add_f32_e32 v132, v132, v133
	v_pk_add_f32 v[134:135], v[134:135], v[134:135] op_sel_hi:[0,1]
	v_add_f32_e32 v133, 0, v132
	v_add_f32_e32 v137, v88, v89
	v_add_f32_e32 v139, v90, v91
	v_mov_b32_e32 v136, v84
	v_mov_b32_e32 v138, v85
	v_mov_b32_e32 v134, v86
	v_mov_b32_e32 v132, v87
	v_pk_add_f32 v[136:137], v[136:137], v[138:139]
	v_pk_add_f32 v[132:133], v[134:135], v[132:133]
	s_nop 0
	v_pk_add_f32 v[132:133], v[136:137], v[132:133]
	s_nop 0
	v_add_f32_e32 v132, v132, v133
	v_mov_b32_e32 v133, v132
	s_nop 1
	v_permlane16_swap_b32_e32 v133, v132
	s_waitcnt lgkmcnt(0)
	v_add_f32_e32 v132, v132, v133
	v_mov_b32_e32 v133, v132
	s_nop 1
	v_permlane32_swap_b32_e32 v133, v132
	s_waitcnt lgkmcnt(0)
	v_add_f32_e32 v132, v132, v133
	v_fmamk_f32 v134, v132, 0xbc800000, v99
	v_fmamk_f32 v136, v132, 0xbc800000, v97
	v_fmamk_f32 v133, v132, 0xbc800000, v98
	v_fmamk_f32 v135, v132, 0xbc800000, v96
	v_mul_f32_e32 v136, v136, v136
	v_mul_f32_e32 v134, v134, v134
	v_fmac_f32_e32 v136, v135, v135
	v_fmac_f32_e32 v134, v133, v133
	v_fmamk_f32 v135, v132, 0xbc800000, v95
	v_fmamk_f32 v137, v132, 0xbc800000, v93
	v_add_f32_e32 v133, v136, v134
	v_fmamk_f32 v134, v132, 0xbc800000, v94
	v_fmamk_f32 v136, v132, 0xbc800000, v92
	v_mul_f32_e32 v137, v137, v137
	v_mul_f32_e32 v135, v135, v135
	v_fmac_f32_e32 v137, v136, v136
	v_fmac_f32_e32 v135, v134, v134
	v_add_f32_e32 v134, v137, v135
	v_fmamk_f32 v135, v132, 0xbc800000, v91
	v_fmamk_f32 v137, v132, 0xbc800000, v89
	v_add_f32_e32 v133, v133, v134
	v_fmamk_f32 v134, v132, 0xbc800000, v90
	v_fmamk_f32 v136, v132, 0xbc800000, v88
	v_mul_f32_e32 v137, v137, v137
	v_mul_f32_e32 v135, v135, v135
	v_fmac_f32_e32 v137, v136, v136
	v_fmac_f32_e32 v135, v134, v134
	v_add_f32_e32 v134, v137, v135
	v_fmamk_f32 v135, v132, 0xbc800000, v87
	v_fmamk_f32 v137, v132, 0xbc800000, v85
	v_add_f32_e32 v133, v134, v133
	v_fmamk_f32 v134, v132, 0xbc800000, v86
	v_fmamk_f32 v136, v132, 0xbc800000, v84
	v_mul_f32_e32 v137, v137, v137
	v_mul_f32_e32 v135, v135, v135
	v_fmac_f32_e32 v137, v136, v136
	v_fmac_f32_e32 v135, v134, v134
	v_add_f32_e32 v134, v137, v135
	v_add_f32_e32 v133, v134, v133
	v_mov_b32_e32 v134, v133
	s_nop 1
	v_permlane16_swap_b32_e32 v134, v133
	s_waitcnt lgkmcnt(0)
	v_add_f32_e32 v133, v133, v134
	v_mov_b32_e32 v134, v133
	s_nop 1
	v_permlane32_swap_b32_e32 v134, v133
	s_and_saveexec_b64 s[62:63], s[4:5]
	s_cbranch_execz .LBB0_718
	v_mul_f32_e32 v132, 0x3c800000, v132
	s_waitcnt lgkmcnt(0)
	v_add_f32_e32 v133, v133, v134
	ds_write_b64 v206, v[132:133] offset:4608

; __device__ __forceinline__ float bflo(unsigned w) { return __uint_as_float(w << 16); }
; __device__ __forceinline__ float bfhi(unsigned w) { return __uint_as_float(w & 0xffff0000u); }
;     __device__ __forceinline__ void operator()(f32x4 (&acc)[2][2][4][2], const Unit& u, int wr, int wc, int fr, int fq, int wid, int lane) const {
;     ...
;             for (int m = 0; m < 4; ++m) { const size_t off = (size_t)(row0 + ai * HALF + m * 16) * D + col0;
; #pragma unroll
;                 for (int bj = 0; bj < 2; ++bj) { f32x4 x0, x1;
;                     if (X) { x0 = *(const f32x4*)(X + off + bj * HALF); x1 = *(const f32x4*)(X + off + bj * HALF + 4); }
;                     else { const u32x4 xw = *(const u32x4*)(XB + off + bj * HALF); x0 = (f32x4){bflo(xw.x), bfhi(xw.x), bflo(xw.y), bfhi(xw.y)}; x1 = (f32x4){bflo(xw.z), bfhi(xw.z), bflo(xw.w), bfhi(xw.w)}; }
;                     acc[ai][bj][m][0] = x0 * ALPHA + acc[ai][bj][m][0]; acc[ai][bj][m][1] = x1 * ALPHA + acc[ai][bj][m][1]; }
;                 asm volatile("" : "+v"(acc[ai][0][m][0]), "+v"(acc[ai][0][m][1]), "+v"(acc[ai][1][m][0]), "+v"(acc[ai][1][m][1]));
;                 float s = 0.f;
; #pragma unroll
;                 for (int bj = 0; bj < 2; ++bj)
; #pragma unroll
;                     for (int n = 0; n < 2; ++n) { const f32x4 x = acc[ai][bj][m][n]; s += (x[0] + x[1]) + (x[2] + x[3]); }
;                 s += __shfl_xor(s, 16); s += __shfl_xor(s, 32);
;                 const float mw = s * (1.0f / 64.0f); float q = 0.f;
; #pragma unroll
;                 for (int bj = 0; bj < 2; ++bj)
; #pragma unroll
;                     for (int n = 0; n < 2; ++n) { const f32x4 d = acc[ai][bj][m][n] - mw; q += (d[0] * d[0] + d[1] * d[1]) + (d[2] * d[2] + d[3] * d[3]); }
;                 q += __shfl_xor(q, 16); q += __shfl_xor(q, 32);
;                 if (fq == 0) P[(ai * HALF + wr * 64 + m * 16 + fr) * 4 + wc] = (f32x2){mw, q};
.LBB0_724:
	s_waitcnt vmcnt(0) lgkmcnt(0)
	v_pk_fma_f32 v[66:67], v[134:135], s[92:93], v[66:67] op_sel_hi:[1,0,1]
	v_pk_fma_f32 v[64:65], v[132:133], s[92:93], v[64:65] op_sel_hi:[1,0,1]
	v_pk_fma_f32 v[62:63], v[138:139], s[92:93], v[62:63] op_sel_hi:[1,0,1]
	v_pk_fma_f32 v[60:61], v[136:137], s[92:93], v[60:61] op_sel_hi:[1,0,1]
	v_pk_fma_f32 v[50:51], v[142:143], s[92:93], v[50:51] op_sel_hi:[1,0,1]
	v_pk_fma_f32 v[48:49], v[140:141], s[92:93], v[48:49] op_sel_hi:[1,0,1]
	v_pk_fma_f32 v[46:47], v[146:147], s[92:93], v[46:47] op_sel_hi:[1,0,1]
	v_pk_fma_f32 v[44:45], v[144:145], s[92:93], v[44:45] op_sel_hi:[1,0,1]
	s_nop 0
	s_nop 0
	v_mov_b32_e32 v132, v65
	v_mov_b32_e32 v133, v66
	v_mov_b32_e32 v134, v64
	v_mov_b32_e32 v135, v67
	v_pk_add_f32 v[132:133], v[132:133], v[134:135]
	v_mov_b32_e32 v134, v61
	v_mov_b32_e32 v135, v62
	v_mov_b32_e32 v136, v60
	v_mov_b32_e32 v137, v63
	v_pk_add_f32 v[134:135], v[134:135], v[136:137]
	v_add_f32_e32 v132, v132, v133
	v_pk_add_f32 v[134:135], v[134:135], v[134:135] op_sel_hi:[0,1]
	v_add_f32_e32 v133, 0, v132
	v_add_f32_e32 v137, v48, v49
	v_add_f32_e32 v139, v50, v51
	v_mov_b32_e32 v136, v44
	v_mov_b32_e32 v138, v45
	v_mov_b32_e32 v134, v46
	v_mov_b32_e32 v132, v47
	v_pk_add_f32 v[136:137], v[136:137], v[138:139]
	v_pk_add_f32 v[132:133], v[134:135], v[132:133]
	s_nop 0
	v_pk_add_f32 v[132:133], v[136:137], v[132:133]
	s_nop 0
	v_add_f32_e32 v132, v132, v133
	v_mov_b32_e32 v133, v132
	s_nop 1
	v_permlane16_swap_b32_e32 v133, v132
	s_waitcnt lgkmcnt(0)
	v_add_f32_e32 v132, v132, v133
	v_mov_b32_e32 v133, v132
	s_nop 1
	v_permlane32_swap_b32_e32 v133, v132
	s_waitcnt lgkmcnt(0)
	v_add_f32_e32 v132, v132, v133
	v_fmamk_f32 v134, v132, 0xbc800000, v67
	v_fmamk_f32 v136, v132, 0xbc800000, v65
	v_fmamk_f32 v133, v132, 0xbc800000, v66
	v_fmamk_f32 v135, v132, 0xbc800000, v64
	v_mul_f32_e32 v136, v136, v136
	v_mul_f32_e32 v134, v134, v134
	v_fmac_f32_e32 v136, v135, v135
	v_fmac_f32_e32 v134, v133, v133
	v_fmamk_f32 v135, v132, 0xbc800000, v63
	v_fmamk_f32 v137, v132, 0xbc800000, v61
	v_add_f32_e32 v133, v136, v134
	v_fmamk_f32 v134, v132, 0xbc800000, v62
	v_fmamk_f32 v136, v132, 0xbc800000, v60
	v_mul_f32_e32 v137, v137, v137
	v_mul_f32_e32 v135, v135, v135
	v_fmac_f32_e32 v137, v136, v136
	v_fmac_f32_e32 v135, v134, v134
	v_add_f32_e32 v134, v137, v135
	v_fmamk_f32 v135, v132, 0xbc800000, v51
	v_fmamk_f32 v137, v132, 0xbc800000, v49
	v_add_f32_e32 v133, v133, v134
	v_fmamk_f32 v134, v132, 0xbc800000, v50
	v_fmamk_f32 v136, v132, 0xbc800000, v48
	v_mul_f32_e32 v137, v137, v137
	v_mul_f32_e32 v135, v135, v135
	v_fmac_f32_e32 v137, v136, v136
	v_fmac_f32_e32 v135, v134, v134
	v_add_f32_e32 v134, v137, v135
	v_fmamk_f32 v135, v132, 0xbc800000, v47
	v_fmamk_f32 v137, v132, 0xbc800000, v45
	v_add_f32_e32 v133, v134, v133
	v_fmamk_f32 v134, v132, 0xbc800000, v46
	v_fmamk_f32 v136, v132, 0xbc800000, v44
	v_mul_f32_e32 v137, v137, v137
	v_mul_f32_e32 v135, v135, v135
	v_fmac_f32_e32 v137, v136, v136
	v_fmac_f32_e32 v135, v134, v134
	v_add_f32_e32 v134, v137, v135
	v_add_f32_e32 v133, v134, v133
	v_mov_b32_e32 v134, v133
	s_nop 1
	v_permlane16_swap_b32_e32 v134, v133
	s_waitcnt lgkmcnt(0)
	v_add_f32_e32 v133, v133, v134
	v_mov_b32_e32 v134, v133
	s_nop 1
	v_permlane32_swap_b32_e32 v134, v133
	s_and_saveexec_b64 s[62:63], s[4:5]
	s_cbranch_execz .LBB0_726
	v_mul_f32_e32 v132, 0x3c800000, v132
	s_waitcnt lgkmcnt(0)
	v_add_f32_e32 v133, v133, v134
	ds_write_b64 v206, v[132:133] offset:5120

; __device__ __forceinline__ float bflo(unsigned w) { return __uint_as_float(w << 16); }
; __device__ __forceinline__ float bfhi(unsigned w) { return __uint_as_float(w & 0xffff0000u); }
;     __device__ __forceinline__ void operator()(f32x4 (&acc)[2][2][4][2], const Unit& u, int wr, int wc, int fr, int fq, int wid, int lane) const {
;     ...
;             for (int m = 0; m < 4; ++m) { const size_t off = (size_t)(row0 + ai * HALF + m * 16) * D + col0;
; #pragma unroll
;                 for (int bj = 0; bj < 2; ++bj) { f32x4 x0, x1;
;                     if (X) { x0 = *(const f32x4*)(X + off + bj * HALF); x1 = *(const f32x4*)(X + off + bj * HALF + 4); }
;                     else { const u32x4 xw = *(const u32x4*)(XB + off + bj * HALF); x0 = (f32x4){bflo(xw.x), bfhi(xw.x), bflo(xw.y), bfhi(xw.y)}; x1 = (f32x4){bflo(xw.z), bfhi(xw.z), bflo(xw.w), bfhi(xw.w)}; }
;                     acc[ai][bj][m][0] = x0 * ALPHA + acc[ai][bj][m][0]; acc[ai][bj][m][1] = x1 * ALPHA + acc[ai][bj][m][1]; }
;                 asm volatile("" : "+v"(acc[ai][0][m][0]), "+v"(acc[ai][0][m][1]), "+v"(acc[ai][1][m][0]), "+v"(acc[ai][1][m][1]));
;                 float s = 0.f;
; #pragma unroll
;                 for (int bj = 0; bj < 2; ++bj)
; #pragma unroll
;                     for (int n = 0; n < 2; ++n) { const f32x4 x = acc[ai][bj][m][n]; s += (x[0] + x[1]) + (x[2] + x[3]); }
;                 s += __shfl_xor(s, 16); s += __shfl_xor(s, 32);
;                 const float mw = s * (1.0f / 64.0f); float q = 0.f;
; #pragma unroll
;                 for (int bj = 0; bj < 2; ++bj)
; #pragma unroll
;                     for (int n = 0; n < 2; ++n) { const f32x4 d = acc[ai][bj][m][n] - mw; q += (d[0] * d[0] + d[1] * d[1]) + (d[2] * d[2] + d[3] * d[3]); }
;                 q += __shfl_xor(q, 16); q += __shfl_xor(q, 32);
;                 if (fq == 0) P[(ai * HALF + wr * 64 + m * 16 + fr) * 4 + wc] = (f32x2){mw, q};
.LBB0_732:
	s_waitcnt vmcnt(0) lgkmcnt(0)
	v_pk_fma_f32 v[26:27], v[134:135], s[92:93], v[26:27] op_sel_hi:[1,0,1]
	v_pk_fma_f32 v[24:25], v[132:133], s[92:93], v[24:25] op_sel_hi:[1,0,1]
	v_pk_fma_f32 v[22:23], v[138:139], s[92:93], v[22:23] op_sel_hi:[1,0,1]
	v_pk_fma_f32 v[20:21], v[136:137], s[92:93], v[20:21] op_sel_hi:[1,0,1]
	v_pk_fma_f32 v[18:19], v[142:143], s[92:93], v[18:19] op_sel_hi:[1,0,1]
	v_pk_fma_f32 v[16:17], v[140:141], s[92:93], v[16:17] op_sel_hi:[1,0,1]
	v_pk_fma_f32 v[14:15], v[146:147], s[92:93], v[14:15] op_sel_hi:[1,0,1]
	v_pk_fma_f32 v[12:13], v[144:145], s[92:93], v[12:13] op_sel_hi:[1,0,1]
	s_nop 0
	s_nop 0
	v_mov_b32_e32 v132, v25
	v_mov_b32_e32 v133, v26
	v_mov_b32_e32 v134, v24
	v_mov_b32_e32 v135, v27
	v_pk_add_f32 v[132:133], v[132:133], v[134:135]
	v_mov_b32_e32 v134, v21
	v_mov_b32_e32 v135, v22
	v_mov_b32_e32 v136, v20
	v_mov_b32_e32 v137, v23
	v_pk_add_f32 v[134:135], v[134:135], v[136:137]
	v_add_f32_e32 v132, v132, v133
	v_pk_add_f32 v[134:135], v[134:135], v[134:135] op_sel_hi:[0,1]
	v_add_f32_e32 v133, 0, v132
	v_add_f32_e32 v137, v16, v17
	v_add_f32_e32 v139, v18, v19
	v_mov_b32_e32 v136, v12
	v_mov_b32_e32 v138, v13
	v_mov_b32_e32 v134, v14
	v_mov_b32_e32 v132, v15
	v_pk_add_f32 v[136:137], v[136:137], v[138:139]
	v_pk_add_f32 v[132:133], v[134:135], v[132:133]
	s_nop 0
	v_pk_add_f32 v[132:133], v[136:137], v[132:133]
	s_nop 0
	v_add_f32_e32 v132, v132, v133
	v_mov_b32_e32 v133, v132
	s_nop 1
	v_permlane16_swap_b32_e32 v133, v132
	s_waitcnt lgkmcnt(0)
	v_add_f32_e32 v132, v132, v133
	v_mov_b32_e32 v133, v132
	s_nop 1
	v_permlane32_swap_b32_e32 v133, v132
	s_waitcnt lgkmcnt(0)
	v_add_f32_e32 v132, v132, v133
	v_fmamk_f32 v134, v132, 0xbc800000, v27
	v_fmamk_f32 v136, v132, 0xbc800000, v25
	v_fmamk_f32 v133, v132, 0xbc800000, v26
	v_fmamk_f32 v135, v132, 0xbc800000, v24
	v_mul_f32_e32 v136, v136, v136
	v_mul_f32_e32 v134, v134, v134
	v_fmac_f32_e32 v136, v135, v135
	v_fmac_f32_e32 v134, v133, v133
	v_fmamk_f32 v135, v132, 0xbc800000, v23
	v_fmamk_f32 v137, v132, 0xbc800000, v21
	v_add_f32_e32 v133, v136, v134
	v_fmamk_f32 v134, v132, 0xbc800000, v22
	v_fmamk_f32 v136, v132, 0xbc800000, v20
	v_mul_f32_e32 v137, v137, v137
	v_mul_f32_e32 v135, v135, v135
	v_fmac_f32_e32 v137, v136, v136
	v_fmac_f32_e32 v135, v134, v134
	v_add_f32_e32 v134, v137, v135
	v_fmamk_f32 v135, v132, 0xbc800000, v19
	v_fmamk_f32 v137, v132, 0xbc800000, v17
	v_add_f32_e32 v133, v133, v134
	v_fmamk_f32 v134, v132, 0xbc800000, v18
	v_fmamk_f32 v136, v132, 0xbc800000, v16
	v_mul_f32_e32 v137, v137, v137
	v_mul_f32_e32 v135, v135, v135
	v_fmac_f32_e32 v137, v136, v136
	v_fmac_f32_e32 v135, v134, v134
	v_add_f32_e32 v134, v137, v135
	v_fmamk_f32 v135, v132, 0xbc800000, v15
	v_fmamk_f32 v137, v132, 0xbc800000, v13
	v_add_f32_e32 v133, v134, v133
	v_fmamk_f32 v134, v132, 0xbc800000, v14
	v_fmamk_f32 v136, v132, 0xbc800000, v12
	v_mul_f32_e32 v137, v137, v137
	v_mul_f32_e32 v135, v135, v135
	v_fmac_f32_e32 v137, v136, v136
	v_fmac_f32_e32 v135, v134, v134
	v_add_f32_e32 v134, v137, v135
	v_add_f32_e32 v133, v134, v133
	v_mov_b32_e32 v134, v133
	s_nop 1
	v_permlane16_swap_b32_e32 v134, v133
	s_waitcnt lgkmcnt(0)
	v_add_f32_e32 v133, v133, v134
	v_mov_b32_e32 v134, v133
	s_nop 1
	v_permlane32_swap_b32_e32 v134, v133
	s_and_saveexec_b64 s[10:11], s[4:5]
	s_cbranch_execz .LBB0_734
	v_mul_f32_e32 v132, 0x3c800000, v132
	s_waitcnt lgkmcnt(0)
	v_add_f32_e32 v133, v133, v134
	ds_write_b64 v206, v[132:133] offset:5632

; __device__ __forceinline__ float bflo(unsigned w) { return __uint_as_float(w << 16); }
; __device__ __forceinline__ float bfhi(unsigned w) { return __uint_as_float(w & 0xffff0000u); }
;     __device__ __forceinline__ void operator()(f32x4 (&acc)[2][2][4][2], const Unit& u, int wr, int wc, int fr, int fq, int wid, int lane) const {
;     ...
;             for (int m = 0; m < 4; ++m) { const size_t off = (size_t)(row0 + ai * HALF + m * 16) * D + col0;
; #pragma unroll
;                 for (int bj = 0; bj < 2; ++bj) { f32x4 x0, x1;
;                     if (X) { x0 = *(const f32x4*)(X + off + bj * HALF); x1 = *(const f32x4*)(X + off + bj * HALF + 4); }
;                     else { const u32x4 xw = *(const u32x4*)(XB + off + bj * HALF); x0 = (f32x4){bflo(xw.x), bfhi(xw.x), bflo(xw.y), bfhi(xw.y)}; x1 = (f32x4){bflo(xw.z), bfhi(xw.z), bflo(xw.w), bfhi(xw.w)}; }
;                     acc[ai][bj][m][0] = x0 * ALPHA + acc[ai][bj][m][0]; acc[ai][bj][m][1] = x1 * ALPHA + acc[ai][bj][m][1]; }
;                 asm volatile("" : "+v"(acc[ai][0][m][0]), "+v"(acc[ai][0][m][1]), "+v"(acc[ai][1][m][0]), "+v"(acc[ai][1][m][1]));
;                 float s = 0.f;
; #pragma unroll
;                 for (int bj = 0; bj < 2; ++bj)
; #pragma unroll
;                     for (int n = 0; n < 2; ++n) { const f32x4 x = acc[ai][bj][m][n]; s += (x[0] + x[1]) + (x[2] + x[3]); }
;                 s += __shfl_xor(s, 16); s += __shfl_xor(s, 32);
;                 const float mw = s * (1.0f / 64.0f); float q = 0.f;
; #pragma unroll
;                 for (int bj = 0; bj < 2; ++bj)
; #pragma unroll
;                     for (int n = 0; n < 2; ++n) { const f32x4 d = acc[ai][bj][m][n] - mw; q += (d[0] * d[0] + d[1] * d[1]) + (d[2] * d[2] + d[3] * d[3]); }
;                 q += __shfl_xor(q, 16); q += __shfl_xor(q, 32);
;                 if (fq == 0) P[(ai * HALF + wr * 64 + m * 16 + fr) * 4 + wc] = (f32x2){mw, q};
.LBB0_1114:
	s_lshl_b32 s82, s84, 8
	v_add_u32_e32 v132, s82, v158
	v_ashrrev_i32_e32 v133, 31, v132
	v_lshlrev_b64 v[172:173], 11, v[132:133]
	v_lshl_add_u64 v[176:177], v[172:173], 0, v[152:153]
	v_lshl_add_u64 v[174:175], v[176:177], 1, s[46:47]
	global_load_dwordx4 v[208:211], v[174:175], off
	global_load_dwordx4 v[212:215], v[174:175], off offset:256
	s_mov_b64 s[10:11], 0x10000
	s_nop 0
	v_lshl_add_u64 v[248:249], v[174:175], 0, s[10:11]
	global_load_dwordx4 v[216:219], v[248:249], off
	global_load_dwordx4 v[220:223], v[248:249], off offset:256
	s_mov_b64 s[10:11], 0x20000
	s_nop 0
	v_lshl_add_u64 v[248:249], v[174:175], 0, s[10:11]
	global_load_dwordx4 v[224:227], v[248:249], off
	global_load_dwordx4 v[228:231], v[248:249], off offset:256
	s_mov_b64 s[10:11], 0x30000
	s_nop 0
	v_lshl_add_u64 v[248:249], v[174:175], 0, s[10:11]
	global_load_dwordx4 v[232:235], v[248:249], off
	global_load_dwordx4 v[236:239], v[248:249], off offset:256
	s_mov_b64 s[10:11], 0x80000
	s_nop 0
	v_lshl_add_u64 v[248:249], v[174:175], 0, s[10:11]
	global_load_dwordx4 v[240:243], v[248:249], off
	global_load_dwordx4 v[244:247], v[248:249], off offset:256
	s_waitcnt vmcnt(9)
	v_mov_b32_e32 v134, v208
	v_mov_b32_e32 v135, v209
	v_mov_b32_e32 v136, v210
	v_mov_b32_e32 v137, v211
	v_lshlrev_b32_e32 v138, 16, v134
	v_and_b32_e32 v139, 0xffff0000, v134
	v_lshlrev_b32_e32 v134, 16, v135
	v_and_b32_e32 v135, 0xffff0000, v135
	v_lshlrev_b32_e32 v140, 16, v136
	v_and_b32_e32 v141, 0xffff0000, v136
	v_lshlrev_b32_e32 v136, 16, v137
	v_and_b32_e32 v137, 0xffff0000, v137
	v_pk_fma_f32 v[18:19], v[134:135], s[92:93], v[18:19] op_sel_hi:[1,0,1]
	v_pk_fma_f32 v[14:15], v[136:137], s[92:93], v[14:15] op_sel_hi:[1,0,1]
	v_pk_fma_f32 v[16:17], v[138:139], s[92:93], v[16:17] op_sel_hi:[1,0,1]
	v_pk_fma_f32 v[12:13], v[140:141], s[92:93], v[12:13] op_sel_hi:[1,0,1]
	s_waitcnt vmcnt(8)
	v_mov_b32_e32 v134, v212
	v_mov_b32_e32 v135, v213
	v_mov_b32_e32 v136, v214
	v_mov_b32_e32 v137, v215
	s_mov_b64 s[10:11], 0x90000
	s_nop 0
	v_lshl_add_u64 v[248:249], v[174:175], 0, s[10:11]
	global_load_dwordx4 v[208:211], v[248:249], off
	global_load_dwordx4 v[212:215], v[248:249], off offset:256
	v_lshlrev_b32_e32 v138, 16, v134
	v_and_b32_e32 v139, 0xffff0000, v134
	v_lshlrev_b32_e32 v134, 16, v135
	v_and_b32_e32 v135, 0xffff0000, v135
	v_lshlrev_b32_e32 v140, 16, v136
	v_and_b32_e32 v141, 0xffff0000, v136
	v_lshlrev_b32_e32 v136, 16, v137
	v_and_b32_e32 v137, 0xffff0000, v137
	v_pk_fma_f32 v[10:11], v[134:135], s[92:93], v[10:11] op_sel_hi:[1,0,1]
	v_pk_fma_f32 v[8:9], v[138:139], s[92:93], v[8:9] op_sel_hi:[1,0,1]
	v_pk_fma_f32 v[6:7], v[136:137], s[92:93], v[6:7] op_sel_hi:[1,0,1]
	v_pk_fma_f32 v[4:5], v[140:141], s[92:93], v[4:5] op_sel_hi:[1,0,1]
	s_nop 0
	s_nop 0
	v_mov_b32_e32 v134, v17
	v_mov_b32_e32 v135, v18
	v_mov_b32_e32 v136, v16
	v_mov_b32_e32 v137, v19
	v_pk_add_f32 v[134:135], v[134:135], v[136:137]
	v_mov_b32_e32 v136, v13
	v_mov_b32_e32 v137, v14
	v_mov_b32_e32 v138, v12
	v_mov_b32_e32 v139, v15
	v_pk_add_f32 v[136:137], v[136:137], v[138:139]
	v_add_f32_e32 v134, v134, v135
	v_pk_add_f32 v[136:137], v[136:137], v[136:137] op_sel_hi:[0,1]
	v_add_f32_e32 v135, 0, v134
	v_add_f32_e32 v139, v8, v9
	v_add_f32_e32 v141, v10, v11
	v_mov_b32_e32 v138, v4
	v_mov_b32_e32 v140, v5
	v_mov_b32_e32 v136, v6
	v_mov_b32_e32 v134, v7
	v_pk_add_f32 v[138:139], v[138:139], v[140:141]
	v_pk_add_f32 v[134:135], v[136:137], v[134:135]
	v_and_b32_e32 v136, 64, v202
	v_pk_add_f32 v[134:135], v[138:139], v[134:135]
	v_add_u32_e32 v137, 64, v136
	v_add_f32_e32 v134, v134, v135
	v_xor_b32_e32 v135, 16, v202
	v_cmp_lt_i32_e32 vcc, v135, v137
	s_nop 1
	v_cndmask_b32_e32 v135, v202, v135, vcc
	v_lshlrev_b32_e32 v136, 2, v135
	v_mov_b32_e32 v135, v134
	s_nop 1
	v_permlane16_swap_b32_e32 v135, v134
	s_waitcnt lgkmcnt(0)
	v_add_f32_e32 v134, v134, v135
	v_xor_b32_e32 v135, 32, v202
	v_cmp_lt_i32_e32 vcc, v135, v137
	s_nop 1
	v_cndmask_b32_e32 v135, v202, v135, vcc
	v_lshlrev_b32_e32 v137, 2, v135
	v_mov_b32_e32 v135, v134
	s_nop 1
	v_permlane32_swap_b32_e32 v135, v134
	s_waitcnt lgkmcnt(0)
	v_add_f32_e32 v134, v134, v135
	v_fmamk_f32 v138, v134, 0xbc800000, v19
	v_fmamk_f32 v140, v134, 0xbc800000, v17
	v_fmamk_f32 v135, v134, 0xbc800000, v18
	v_fmamk_f32 v139, v134, 0xbc800000, v16
	v_mul_f32_e32 v140, v140, v140
	v_mul_f32_e32 v138, v138, v138
	v_fmac_f32_e32 v140, v139, v139
	v_fmac_f32_e32 v138, v135, v135
	v_fmamk_f32 v139, v134, 0xbc800000, v15
	v_fmamk_f32 v141, v134, 0xbc800000, v13
	v_add_f32_e32 v135, v140, v138
	v_fmamk_f32 v138, v134, 0xbc800000, v14
	v_fmamk_f32 v140, v134, 0xbc800000, v12
	v_mul_f32_e32 v141, v141, v141
	v_mul_f32_e32 v139, v139, v139
	v_fmac_f32_e32 v141, v140, v140
	v_fmac_f32_e32 v139, v138, v138
	v_add_f32_e32 v138, v141, v139
	v_fmamk_f32 v139, v134, 0xbc800000, v11
	v_fmamk_f32 v141, v134, 0xbc800000, v9
	v_add_f32_e32 v135, v135, v138
	v_fmamk_f32 v138, v134, 0xbc800000, v10
	v_fmamk_f32 v140, v134, 0xbc800000, v8
	v_mul_f32_e32 v141, v141, v141
	v_mul_f32_e32 v139, v139, v139
	v_fmac_f32_e32 v141, v140, v140
	v_fmac_f32_e32 v139, v138, v138
	v_add_f32_e32 v138, v141, v139
	v_fmamk_f32 v139, v134, 0xbc800000, v7
	v_fmamk_f32 v141, v134, 0xbc800000, v5
	v_add_f32_e32 v135, v138, v135
	v_fmamk_f32 v138, v134, 0xbc800000, v6
	v_fmamk_f32 v140, v134, 0xbc800000, v4
	v_mul_f32_e32 v141, v141, v141
	v_mul_f32_e32 v139, v139, v139
	v_fmac_f32_e32 v141, v140, v140
	v_fmac_f32_e32 v139, v138, v138
	v_add_f32_e32 v138, v141, v139
	v_add_f32_e32 v135, v138, v135
	v_mov_b32_e32 v138, v135
	s_nop 1
	v_permlane16_swap_b32_e32 v138, v135
	s_waitcnt lgkmcnt(0)
	v_add_f32_e32 v135, v135, v138
	v_mov_b32_e32 v138, v135
	s_nop 1
	v_permlane32_swap_b32_e32 v138, v135
	s_and_saveexec_b64 s[10:11], s[4:5]
	s_cbranch_execz .LBB0_1116
	v_mul_f32_e32 v134, 0x3c800000, v134
	s_waitcnt lgkmcnt(0)
	v_add_f32_e32 v135, v135, v138
	ds_write_b64 v206, v[134:135]
; __device__ __forceinline__ float bflo(unsigned w) { return __uint_as_float(w << 16); }
; __device__ __forceinline__ float bfhi(unsigned w) { return __uint_as_float(w & 0xffff0000u); }
;     __device__ __forceinline__ void operator()(f32x4 (&acc)[2][2][4][2], const Unit& u, int wr, int wc, int fr, int fq, int wid, int lane) const {
;     ...
;             for (int m = 0; m < 4; ++m) { const size_t off = (size_t)(row0 + ai * HALF + m * 16) * D + col0;
; #pragma unroll
;                 for (int bj = 0; bj < 2; ++bj) { f32x4 x0, x1;
;                     if (X) { x0 = *(const f32x4*)(X + off + bj * HALF); x1 = *(const f32x4*)(X + off + bj * HALF + 4); }
;                     else { const u32x4 xw = *(const u32x4*)(XB + off + bj * HALF); x0 = (f32x4){bflo(xw.x), bfhi(xw.x), bflo(xw.y), bfhi(xw.y)}; x1 = (f32x4){bflo(xw.z), bfhi(xw.z), bflo(xw.w), bfhi(xw.w)}; }
;                     acc[ai][bj][m][0] = x0 * ALPHA + acc[ai][bj][m][0]; acc[ai][bj][m][1] = x1 * ALPHA + acc[ai][bj][m][1]; }
;                 asm volatile("" : "+v"(acc[ai][0][m][0]), "+v"(acc[ai][0][m][1]), "+v"(acc[ai][1][m][0]), "+v"(acc[ai][1][m][1]));
;                 float s = 0.f;
; #pragma unroll
;                 for (int bj = 0; bj < 2; ++bj)
; #pragma unroll
;                     for (int n = 0; n < 2; ++n) { const f32x4 x = acc[ai][bj][m][n]; s += (x[0] + x[1]) + (x[2] + x[3]); }
;                 s += __shfl_xor(s, 16); s += __shfl_xor(s, 32);
;                 const float mw = s * (1.0f / 64.0f); float q = 0.f;
; #pragma unroll
;                 for (int bj = 0; bj < 2; ++bj)
; #pragma unroll
;                     for (int n = 0; n < 2; ++n) { const f32x4 d = acc[ai][bj][m][n] - mw; q += (d[0] * d[0] + d[1] * d[1]) + (d[2] * d[2] + d[3] * d[3]); }
;                 q += __shfl_xor(q, 16); q += __shfl_xor(q, 32);
;                 if (fq == 0) P[(ai * HALF + wr * 64 + m * 16 + fr) * 4 + wc] = (f32x2){mw, q};
.LBB0_1116:
	s_or_b64 exec, exec, s[10:11]
	v_or_b32_e32 v134, 16, v132
	v_ashrrev_i32_e32 v135, 31, v134
	v_lshlrev_b64 v[134:135], 12, v[134:135]
	v_lshl_add_u64 v[134:135], v[166:167], 0, v[134:135]
	s_waitcnt lgkmcnt(0)
	s_waitcnt vmcnt(9)
	v_mov_b32_e32 v138, v216
	v_mov_b32_e32 v139, v217
	v_mov_b32_e32 v140, v218
	v_mov_b32_e32 v141, v219
	v_lshlrev_b32_e32 v142, 16, v138
	v_and_b32_e32 v143, 0xffff0000, v138
	v_lshlrev_b32_e32 v138, 16, v139
	v_and_b32_e32 v139, 0xffff0000, v139
	v_lshlrev_b32_e32 v144, 16, v140
	v_and_b32_e32 v145, 0xffff0000, v140
	v_lshlrev_b32_e32 v140, 16, v141
	v_and_b32_e32 v141, 0xffff0000, v141
	v_pk_fma_f32 v[58:59], v[138:139], s[92:93], v[58:59] op_sel_hi:[1,0,1]
	v_pk_fma_f32 v[54:55], v[140:141], s[92:93], v[54:55] op_sel_hi:[1,0,1]
	v_pk_fma_f32 v[56:57], v[142:143], s[92:93], v[56:57] op_sel_hi:[1,0,1]
	v_pk_fma_f32 v[52:53], v[144:145], s[92:93], v[52:53] op_sel_hi:[1,0,1]
	s_waitcnt vmcnt(8)
	v_mov_b32_e32 v138, v220
	v_mov_b32_e32 v139, v221
	v_mov_b32_e32 v140, v222
	v_mov_b32_e32 v141, v223
	s_mov_b64 s[10:11], 0xa0000
	s_nop 0
	v_lshl_add_u64 v[248:249], v[174:175], 0, s[10:11]
	global_load_dwordx4 v[216:219], v[248:249], off
	global_load_dwordx4 v[220:223], v[248:249], off offset:256
	v_lshlrev_b32_e32 v134, 16, v138
	v_and_b32_e32 v135, 0xffff0000, v138
	v_lshlrev_b32_e32 v138, 16, v139
	v_and_b32_e32 v139, 0xffff0000, v139
	v_lshlrev_b32_e32 v142, 16, v140
	v_and_b32_e32 v143, 0xffff0000, v140
	v_lshlrev_b32_e32 v140, 16, v141
	v_and_b32_e32 v141, 0xffff0000, v141
	v_pk_fma_f32 v[42:43], v[138:139], s[92:93], v[42:43] op_sel_hi:[1,0,1]
	v_pk_fma_f32 v[40:41], v[134:135], s[92:93], v[40:41] op_sel_hi:[1,0,1]
	v_pk_fma_f32 v[38:39], v[140:141], s[92:93], v[38:39] op_sel_hi:[1,0,1]
	v_pk_fma_f32 v[36:37], v[142:143], s[92:93], v[36:37] op_sel_hi:[1,0,1]
	s_nop 0
	s_nop 0
	v_mov_b32_e32 v134, v57
	v_mov_b32_e32 v135, v58
	v_mov_b32_e32 v138, v56
	v_mov_b32_e32 v139, v59
	v_pk_add_f32 v[134:135], v[134:135], v[138:139]
	v_mov_b32_e32 v138, v53
	v_mov_b32_e32 v139, v54
	v_mov_b32_e32 v140, v52
	v_mov_b32_e32 v141, v55
	v_pk_add_f32 v[138:139], v[138:139], v[140:141]
	v_add_f32_e32 v134, v134, v135
	v_pk_add_f32 v[138:139], v[138:139], v[138:139] op_sel_hi:[0,1]
	v_add_f32_e32 v135, 0, v134
	v_add_f32_e32 v141, v40, v41
	v_add_f32_e32 v143, v42, v43
	v_mov_b32_e32 v140, v36
	v_mov_b32_e32 v142, v37
	v_mov_b32_e32 v138, v38
	v_mov_b32_e32 v134, v39
	v_pk_add_f32 v[140:141], v[140:141], v[142:143]
	v_pk_add_f32 v[134:135], v[138:139], v[134:135]
	s_nop 0
	v_pk_add_f32 v[134:135], v[140:141], v[134:135]
	s_nop 0
	v_add_f32_e32 v134, v134, v135
	v_mov_b32_e32 v135, v134
	s_nop 1
	v_permlane16_swap_b32_e32 v135, v134
	s_waitcnt lgkmcnt(0)
	v_add_f32_e32 v134, v134, v135
	v_mov_b32_e32 v135, v134
	s_nop 1
	v_permlane32_swap_b32_e32 v135, v134
	s_waitcnt lgkmcnt(0)
	v_add_f32_e32 v134, v134, v135
	v_fmamk_f32 v138, v134, 0xbc800000, v59
	v_fmamk_f32 v140, v134, 0xbc800000, v57
	v_fmamk_f32 v135, v134, 0xbc800000, v58
	v_fmamk_f32 v139, v134, 0xbc800000, v56
	v_mul_f32_e32 v140, v140, v140
	v_mul_f32_e32 v138, v138, v138
	v_fmac_f32_e32 v140, v139, v139
	v_fmac_f32_e32 v138, v135, v135
	v_fmamk_f32 v139, v134, 0xbc800000, v55
	v_fmamk_f32 v141, v134, 0xbc800000, v53
	v_add_f32_e32 v135, v140, v138
	v_fmamk_f32 v138, v134, 0xbc800000, v54
	v_fmamk_f32 v140, v134, 0xbc800000, v52
	v_mul_f32_e32 v141, v141, v141
	v_mul_f32_e32 v139, v139, v139
	v_fmac_f32_e32 v141, v140, v140
	v_fmac_f32_e32 v139, v138, v138
	v_add_f32_e32 v138, v141, v139
	v_fmamk_f32 v139, v134, 0xbc800000, v43
	v_fmamk_f32 v141, v134, 0xbc800000, v41
	v_add_f32_e32 v135, v135, v138
	v_fmamk_f32 v138, v134, 0xbc800000, v42
	v_fmamk_f32 v140, v134, 0xbc800000, v40
	v_mul_f32_e32 v141, v141, v141
	v_mul_f32_e32 v139, v139, v139
	v_fmac_f32_e32 v141, v140, v140
	v_fmac_f32_e32 v139, v138, v138
	v_add_f32_e32 v138, v141, v139
	v_fmamk_f32 v139, v134, 0xbc800000, v39
	v_fmamk_f32 v141, v134, 0xbc800000, v37
	v_add_f32_e32 v135, v138, v135
	v_fmamk_f32 v138, v134, 0xbc800000, v38
	v_fmamk_f32 v140, v134, 0xbc800000, v36
	v_mul_f32_e32 v141, v141, v141
	v_mul_f32_e32 v139, v139, v139
	v_fmac_f32_e32 v141, v140, v140
	v_fmac_f32_e32 v139, v138, v138
	v_add_f32_e32 v138, v141, v139
	v_add_f32_e32 v135, v138, v135
	v_mov_b32_e32 v138, v135
	s_nop 1
	v_permlane16_swap_b32_e32 v138, v135
	s_waitcnt lgkmcnt(0)
	v_add_f32_e32 v135, v135, v138
	v_mov_b32_e32 v138, v135
	s_nop 1
	v_permlane32_swap_b32_e32 v138, v135
	s_and_saveexec_b64 s[10:11], s[4:5]
	s_cbranch_execz .LBB0_1118
	v_mul_f32_e32 v134, 0x3c800000, v134
	s_waitcnt lgkmcnt(0)
	v_add_f32_e32 v135, v135, v138
	ds_write_b64 v206, v[134:135] offset:512
; __device__ __forceinline__ float bflo(unsigned w) { return __uint_as_float(w << 16); }
; __device__ __forceinline__ float bfhi(unsigned w) { return __uint_as_float(w & 0xffff0000u); }
;     __device__ __forceinline__ void operator()(f32x4 (&acc)[2][2][4][2], const Unit& u, int wr, int wc, int fr, int fq, int wid, int lane) const {
;     ...
;             for (int m = 0; m < 4; ++m) { const size_t off = (size_t)(row0 + ai * HALF + m * 16) * D + col0;
; #pragma unroll
;                 for (int bj = 0; bj < 2; ++bj) { f32x4 x0, x1;
;                     if (X) { x0 = *(const f32x4*)(X + off + bj * HALF); x1 = *(const f32x4*)(X + off + bj * HALF + 4); }
;                     else { const u32x4 xw = *(const u32x4*)(XB + off + bj * HALF); x0 = (f32x4){bflo(xw.x), bfhi(xw.x), bflo(xw.y), bfhi(xw.y)}; x1 = (f32x4){bflo(xw.z), bfhi(xw.z), bflo(xw.w), bfhi(xw.w)}; }
;                     acc[ai][bj][m][0] = x0 * ALPHA + acc[ai][bj][m][0]; acc[ai][bj][m][1] = x1 * ALPHA + acc[ai][bj][m][1]; }
;                 asm volatile("" : "+v"(acc[ai][0][m][0]), "+v"(acc[ai][0][m][1]), "+v"(acc[ai][1][m][0]), "+v"(acc[ai][1][m][1]));
;                 float s = 0.f;
; #pragma unroll
;                 for (int bj = 0; bj < 2; ++bj)
; #pragma unroll
;                     for (int n = 0; n < 2; ++n) { const f32x4 x = acc[ai][bj][m][n]; s += (x[0] + x[1]) + (x[2] + x[3]); }
;                 s += __shfl_xor(s, 16); s += __shfl_xor(s, 32);
;                 const float mw = s * (1.0f / 64.0f); float q = 0.f;
; #pragma unroll
;                 for (int bj = 0; bj < 2; ++bj)
; #pragma unroll
;                     for (int n = 0; n < 2; ++n) { const f32x4 d = acc[ai][bj][m][n] - mw; q += (d[0] * d[0] + d[1] * d[1]) + (d[2] * d[2] + d[3] * d[3]); }
;                 q += __shfl_xor(q, 16); q += __shfl_xor(q, 32);
;                 if (fq == 0) P[(ai * HALF + wr * 64 + m * 16 + fr) * 4 + wc] = (f32x2){mw, q};
.LBB0_1118:
	s_or_b64 exec, exec, s[10:11]
	v_or_b32_e32 v134, 32, v132
	v_ashrrev_i32_e32 v135, 31, v134
	v_lshlrev_b64 v[134:135], 12, v[134:135]
	v_lshl_add_u64 v[134:135], v[166:167], 0, v[134:135]
	s_waitcnt lgkmcnt(0)
	s_waitcnt vmcnt(9)
	v_mov_b32_e32 v138, v224
	v_mov_b32_e32 v139, v225
	v_mov_b32_e32 v140, v226
	v_mov_b32_e32 v141, v227
	v_lshlrev_b32_e32 v142, 16, v138
	v_and_b32_e32 v143, 0xffff0000, v138
	v_lshlrev_b32_e32 v138, 16, v139
	v_and_b32_e32 v139, 0xffff0000, v139
	v_lshlrev_b32_e32 v144, 16, v140
	v_and_b32_e32 v145, 0xffff0000, v140
	v_lshlrev_b32_e32 v140, 16, v141
	v_and_b32_e32 v141, 0xffff0000, v141
	v_pk_fma_f32 v[90:91], v[138:139], s[92:93], v[90:91] op_sel_hi:[1,0,1]
	v_pk_fma_f32 v[78:79], v[140:141], s[92:93], v[78:79] op_sel_hi:[1,0,1]
	v_pk_fma_f32 v[88:89], v[142:143], s[92:93], v[88:89] op_sel_hi:[1,0,1]
	v_pk_fma_f32 v[76:77], v[144:145], s[92:93], v[76:77] op_sel_hi:[1,0,1]
	s_waitcnt vmcnt(8)
	v_mov_b32_e32 v138, v228
	v_mov_b32_e32 v139, v229
	v_mov_b32_e32 v140, v230
	v_mov_b32_e32 v141, v231
	s_mov_b64 s[10:11], 0xb0000
	s_nop 0
	v_lshl_add_u64 v[248:249], v[174:175], 0, s[10:11]
	global_load_dwordx4 v[224:227], v[248:249], off
	global_load_dwordx4 v[228:231], v[248:249], off offset:256
	v_lshlrev_b32_e32 v134, 16, v138
	v_and_b32_e32 v135, 0xffff0000, v138
	v_lshlrev_b32_e32 v138, 16, v139
	v_and_b32_e32 v139, 0xffff0000, v139
	v_lshlrev_b32_e32 v142, 16, v140
	v_and_b32_e32 v143, 0xffff0000, v140
	v_lshlrev_b32_e32 v140, 16, v141
	v_and_b32_e32 v141, 0xffff0000, v141
	v_pk_fma_f32 v[66:67], v[138:139], s[92:93], v[66:67] op_sel_hi:[1,0,1]
	v_pk_fma_f32 v[64:65], v[134:135], s[92:93], v[64:65] op_sel_hi:[1,0,1]
	v_pk_fma_f32 v[62:63], v[140:141], s[92:93], v[62:63] op_sel_hi:[1,0,1]
	v_pk_fma_f32 v[60:61], v[142:143], s[92:93], v[60:61] op_sel_hi:[1,0,1]
	s_nop 0
	s_nop 0
	v_mov_b32_e32 v134, v89
	v_mov_b32_e32 v135, v90
	v_mov_b32_e32 v138, v88
	v_mov_b32_e32 v139, v91
	v_pk_add_f32 v[134:135], v[134:135], v[138:139]
	v_mov_b32_e32 v138, v77
	v_mov_b32_e32 v139, v78
	v_mov_b32_e32 v140, v76
	v_mov_b32_e32 v141, v79
	v_pk_add_f32 v[138:139], v[138:139], v[140:141]
	v_add_f32_e32 v134, v134, v135
	v_pk_add_f32 v[138:139], v[138:139], v[138:139] op_sel_hi:[0,1]
	v_add_f32_e32 v135, 0, v134
	v_add_f32_e32 v141, v64, v65
	v_add_f32_e32 v143, v66, v67
	v_mov_b32_e32 v140, v60
	v_mov_b32_e32 v142, v61
	v_mov_b32_e32 v138, v62
	v_mov_b32_e32 v134, v63
	v_pk_add_f32 v[140:141], v[140:141], v[142:143]
	v_pk_add_f32 v[134:135], v[138:139], v[134:135]
	s_nop 0
	v_pk_add_f32 v[134:135], v[140:141], v[134:135]
	s_nop 0
	v_add_f32_e32 v134, v134, v135
	v_mov_b32_e32 v135, v134
	s_nop 1
	v_permlane16_swap_b32_e32 v135, v134
	s_waitcnt lgkmcnt(0)
	v_add_f32_e32 v134, v134, v135
	v_mov_b32_e32 v135, v134
	s_nop 1
	v_permlane32_swap_b32_e32 v135, v134
	s_waitcnt lgkmcnt(0)
	v_add_f32_e32 v134, v134, v135
	v_fmamk_f32 v138, v134, 0xbc800000, v91
	v_fmamk_f32 v140, v134, 0xbc800000, v89
	v_fmamk_f32 v135, v134, 0xbc800000, v90
	v_fmamk_f32 v139, v134, 0xbc800000, v88
	v_mul_f32_e32 v140, v140, v140
	v_mul_f32_e32 v138, v138, v138
	v_fmac_f32_e32 v140, v139, v139
	v_fmac_f32_e32 v138, v135, v135
	v_fmamk_f32 v139, v134, 0xbc800000, v79
	v_fmamk_f32 v141, v134, 0xbc800000, v77
	v_add_f32_e32 v135, v140, v138
	v_fmamk_f32 v138, v134, 0xbc800000, v78
	v_fmamk_f32 v140, v134, 0xbc800000, v76
	v_mul_f32_e32 v141, v141, v141
	v_mul_f32_e32 v139, v139, v139
	v_fmac_f32_e32 v141, v140, v140
	v_fmac_f32_e32 v139, v138, v138
	v_add_f32_e32 v138, v141, v139
	v_fmamk_f32 v139, v134, 0xbc800000, v67
	v_fmamk_f32 v141, v134, 0xbc800000, v65
	v_add_f32_e32 v135, v135, v138
	v_fmamk_f32 v138, v134, 0xbc800000, v66
	v_fmamk_f32 v140, v134, 0xbc800000, v64
	v_mul_f32_e32 v141, v141, v141
	v_mul_f32_e32 v139, v139, v139
	v_fmac_f32_e32 v141, v140, v140
	v_fmac_f32_e32 v139, v138, v138
	v_add_f32_e32 v138, v141, v139
	v_fmamk_f32 v139, v134, 0xbc800000, v63
	v_fmamk_f32 v141, v134, 0xbc800000, v61
	v_add_f32_e32 v135, v138, v135
	v_fmamk_f32 v138, v134, 0xbc800000, v62
	v_fmamk_f32 v140, v134, 0xbc800000, v60
	v_mul_f32_e32 v141, v141, v141
	v_mul_f32_e32 v139, v139, v139
	v_fmac_f32_e32 v141, v140, v140
	v_fmac_f32_e32 v139, v138, v138
	v_add_f32_e32 v138, v141, v139
	v_add_f32_e32 v135, v138, v135
	v_mov_b32_e32 v138, v135
	s_nop 1
	v_permlane16_swap_b32_e32 v138, v135
	s_waitcnt lgkmcnt(0)
	v_add_f32_e32 v135, v135, v138
	v_mov_b32_e32 v138, v135
	s_nop 1
	v_permlane32_swap_b32_e32 v138, v135
	s_and_saveexec_b64 s[10:11], s[4:5]
	s_cbranch_execz .LBB0_1120
	v_mul_f32_e32 v134, 0x3c800000, v134
	s_waitcnt lgkmcnt(0)
	v_add_f32_e32 v135, v135, v138
	ds_write_b64 v206, v[134:135] offset:1024
; __device__ __forceinline__ float bflo(unsigned w) { return __uint_as_float(w << 16); }
; __device__ __forceinline__ float bfhi(unsigned w) { return __uint_as_float(w & 0xffff0000u); }
;     __device__ __forceinline__ void operator()(f32x4 (&acc)[2][2][4][2], const Unit& u, int wr, int wc, int fr, int fq, int wid, int lane) const {
;     ...
;             for (int m = 0; m < 4; ++m) { const size_t off = (size_t)(row0 + ai * HALF + m * 16) * D + col0;
; #pragma unroll
;                 for (int bj = 0; bj < 2; ++bj) { f32x4 x0, x1;
;                     if (X) { x0 = *(const f32x4*)(X + off + bj * HALF); x1 = *(const f32x4*)(X + off + bj * HALF + 4); }
;                     else { const u32x4 xw = *(const u32x4*)(XB + off + bj * HALF); x0 = (f32x4){bflo(xw.x), bfhi(xw.x), bflo(xw.y), bfhi(xw.y)}; x1 = (f32x4){bflo(xw.z), bfhi(xw.z), bflo(xw.w), bfhi(xw.w)}; }
;                     acc[ai][bj][m][0] = x0 * ALPHA + acc[ai][bj][m][0]; acc[ai][bj][m][1] = x1 * ALPHA + acc[ai][bj][m][1]; }
;                 asm volatile("" : "+v"(acc[ai][0][m][0]), "+v"(acc[ai][0][m][1]), "+v"(acc[ai][1][m][0]), "+v"(acc[ai][1][m][1]));
;                 float s = 0.f;
; #pragma unroll
;                 for (int bj = 0; bj < 2; ++bj)
; #pragma unroll
;                     for (int n = 0; n < 2; ++n) { const f32x4 x = acc[ai][bj][m][n]; s += (x[0] + x[1]) + (x[2] + x[3]); }
;                 s += __shfl_xor(s, 16); s += __shfl_xor(s, 32);
;                 const float mw = s * (1.0f / 64.0f); float q = 0.f;
; #pragma unroll
;                 for (int bj = 0; bj < 2; ++bj)
; #pragma unroll
;                     for (int n = 0; n < 2; ++n) { const f32x4 d = acc[ai][bj][m][n] - mw; q += (d[0] * d[0] + d[1] * d[1]) + (d[2] * d[2] + d[3] * d[3]); }
;                 q += __shfl_xor(q, 16); q += __shfl_xor(q, 32);
;                 if (fq == 0) P[(ai * HALF + wr * 64 + m * 16 + fr) * 4 + wc] = (f32x2){mw, q};
.LBB0_1120:
	s_or_b64 exec, exec, s[10:11]
	v_or_b32_e32 v134, 48, v132
	v_ashrrev_i32_e32 v135, 31, v134
	v_lshlrev_b64 v[134:135], 12, v[134:135]
	v_lshl_add_u64 v[134:135], v[166:167], 0, v[134:135]
	s_waitcnt lgkmcnt(0)
	s_waitcnt vmcnt(9)
	v_mov_b32_e32 v138, v232
	v_mov_b32_e32 v139, v233
	v_mov_b32_e32 v140, v234
	v_mov_b32_e32 v141, v235
	v_lshlrev_b32_e32 v142, 16, v138
	v_and_b32_e32 v143, 0xffff0000, v138
	v_lshlrev_b32_e32 v138, 16, v139
	v_and_b32_e32 v139, 0xffff0000, v139
	v_lshlrev_b32_e32 v144, 16, v140
	v_and_b32_e32 v145, 0xffff0000, v140
	v_lshlrev_b32_e32 v140, 16, v141
	v_and_b32_e32 v141, 0xffff0000, v141
	v_pk_fma_f32 v[114:115], v[138:139], s[92:93], v[114:115] op_sel_hi:[1,0,1]
	v_pk_fma_f32 v[110:111], v[140:141], s[92:93], v[110:111] op_sel_hi:[1,0,1]
	v_pk_fma_f32 v[112:113], v[142:143], s[92:93], v[112:113] op_sel_hi:[1,0,1]
	v_pk_fma_f32 v[108:109], v[144:145], s[92:93], v[108:109] op_sel_hi:[1,0,1]
	s_waitcnt vmcnt(8)
	v_mov_b32_e32 v138, v236
	v_mov_b32_e32 v139, v237
	v_mov_b32_e32 v140, v238
	v_mov_b32_e32 v141, v239
	v_lshlrev_b32_e32 v134, 16, v138
	v_and_b32_e32 v135, 0xffff0000, v138
	v_lshlrev_b32_e32 v138, 16, v139
	v_and_b32_e32 v139, 0xffff0000, v139
	v_lshlrev_b32_e32 v142, 16, v140
	v_and_b32_e32 v143, 0xffff0000, v140
	v_lshlrev_b32_e32 v140, 16, v141
	v_and_b32_e32 v141, 0xffff0000, v141
	v_pk_fma_f32 v[98:99], v[138:139], s[92:93], v[98:99] op_sel_hi:[1,0,1]
	v_pk_fma_f32 v[96:97], v[134:135], s[92:93], v[96:97] op_sel_hi:[1,0,1]
	v_pk_fma_f32 v[94:95], v[140:141], s[92:93], v[94:95] op_sel_hi:[1,0,1]
	v_pk_fma_f32 v[92:93], v[142:143], s[92:93], v[92:93] op_sel_hi:[1,0,1]
	s_nop 0
	s_nop 0
	v_mov_b32_e32 v134, v113
	v_mov_b32_e32 v135, v114
	v_mov_b32_e32 v138, v112
	v_mov_b32_e32 v139, v115
	v_pk_add_f32 v[134:135], v[134:135], v[138:139]
	v_mov_b32_e32 v138, v109
	v_mov_b32_e32 v139, v110
	v_mov_b32_e32 v140, v108
	v_mov_b32_e32 v141, v111
	v_pk_add_f32 v[138:139], v[138:139], v[140:141]
	v_add_f32_e32 v134, v134, v135
	v_pk_add_f32 v[138:139], v[138:139], v[138:139] op_sel_hi:[0,1]
	v_add_f32_e32 v135, 0, v134
	v_add_f32_e32 v141, v96, v97
	v_add_f32_e32 v143, v98, v99
	v_mov_b32_e32 v140, v92
	v_mov_b32_e32 v142, v93
	v_mov_b32_e32 v138, v94
	v_mov_b32_e32 v134, v95
	v_pk_add_f32 v[140:141], v[140:141], v[142:143]
	v_pk_add_f32 v[134:135], v[138:139], v[134:135]
	s_nop 0
	v_pk_add_f32 v[134:135], v[140:141], v[134:135]
	s_nop 0
	v_add_f32_e32 v134, v134, v135
	v_mov_b32_e32 v135, v134
	s_nop 1
	v_permlane16_swap_b32_e32 v135, v134
	s_waitcnt lgkmcnt(0)
	v_add_f32_e32 v134, v134, v135
	v_mov_b32_e32 v135, v134
	s_nop 1
	v_permlane32_swap_b32_e32 v135, v134
	s_waitcnt lgkmcnt(0)
	v_add_f32_e32 v134, v134, v135
	v_fmamk_f32 v138, v134, 0xbc800000, v115
	v_fmamk_f32 v140, v134, 0xbc800000, v113
	v_fmamk_f32 v135, v134, 0xbc800000, v114
	v_fmamk_f32 v139, v134, 0xbc800000, v112
	v_mul_f32_e32 v140, v140, v140
	v_mul_f32_e32 v138, v138, v138
	v_fmac_f32_e32 v140, v139, v139
	v_fmac_f32_e32 v138, v135, v135
	v_fmamk_f32 v139, v134, 0xbc800000, v111
	v_fmamk_f32 v141, v134, 0xbc800000, v109
	v_add_f32_e32 v135, v140, v138
	v_fmamk_f32 v138, v134, 0xbc800000, v110
	v_fmamk_f32 v140, v134, 0xbc800000, v108
	v_mul_f32_e32 v141, v141, v141
	v_mul_f32_e32 v139, v139, v139
	v_fmac_f32_e32 v141, v140, v140
	v_fmac_f32_e32 v139, v138, v138
	v_add_f32_e32 v138, v141, v139
	v_fmamk_f32 v139, v134, 0xbc800000, v99
	v_fmamk_f32 v141, v134, 0xbc800000, v97
	v_add_f32_e32 v135, v135, v138
	v_fmamk_f32 v138, v134, 0xbc800000, v98
	v_fmamk_f32 v140, v134, 0xbc800000, v96
	v_mul_f32_e32 v141, v141, v141
	v_mul_f32_e32 v139, v139, v139
	v_fmac_f32_e32 v141, v140, v140
	v_fmac_f32_e32 v139, v138, v138
	v_add_f32_e32 v138, v141, v139
	v_fmamk_f32 v139, v134, 0xbc800000, v95
	v_fmamk_f32 v141, v134, 0xbc800000, v93
	v_add_f32_e32 v135, v138, v135
	v_fmamk_f32 v138, v134, 0xbc800000, v94
	v_fmamk_f32 v140, v134, 0xbc800000, v92
	v_mul_f32_e32 v141, v141, v141
	v_mul_f32_e32 v139, v139, v139
	v_fmac_f32_e32 v141, v140, v140
	v_fmac_f32_e32 v139, v138, v138
	v_add_f32_e32 v138, v141, v139
	v_add_f32_e32 v135, v138, v135
	v_mov_b32_e32 v138, v135
	s_nop 1
	v_permlane16_swap_b32_e32 v138, v135
	s_waitcnt lgkmcnt(0)
	v_add_f32_e32 v135, v135, v138
	v_mov_b32_e32 v138, v135
	s_nop 1
	v_permlane32_swap_b32_e32 v138, v135
	s_and_saveexec_b64 s[10:11], s[4:5]
	s_cbranch_execz .LBB0_1122
	v_mul_f32_e32 v134, 0x3c800000, v134
	s_waitcnt lgkmcnt(0)
	v_add_f32_e32 v135, v135, v138
	ds_write_b64 v206, v[134:135] offset:1536
; __device__ __forceinline__ float bflo(unsigned w) { return __uint_as_float(w << 16); }
; __device__ __forceinline__ float bfhi(unsigned w) { return __uint_as_float(w & 0xffff0000u); }
;     __device__ __forceinline__ void operator()(f32x4 (&acc)[2][2][4][2], const Unit& u, int wr, int wc, int fr, int fq, int wid, int lane) const {
;     ...
;             for (int m = 0; m < 4; ++m) { const size_t off = (size_t)(row0 + ai * HALF + m * 16) * D + col0;
; #pragma unroll
;                 for (int bj = 0; bj < 2; ++bj) { f32x4 x0, x1;
;                     if (X) { x0 = *(const f32x4*)(X + off + bj * HALF); x1 = *(const f32x4*)(X + off + bj * HALF + 4); }
;                     else { const u32x4 xw = *(const u32x4*)(XB + off + bj * HALF); x0 = (f32x4){bflo(xw.x), bfhi(xw.x), bflo(xw.y), bfhi(xw.y)}; x1 = (f32x4){bflo(xw.z), bfhi(xw.z), bflo(xw.w), bfhi(xw.w)}; }
;                     acc[ai][bj][m][0] = x0 * ALPHA + acc[ai][bj][m][0]; acc[ai][bj][m][1] = x1 * ALPHA + acc[ai][bj][m][1]; }
;                 asm volatile("" : "+v"(acc[ai][0][m][0]), "+v"(acc[ai][0][m][1]), "+v"(acc[ai][1][m][0]), "+v"(acc[ai][1][m][1]));
;                 float s = 0.f;
; #pragma unroll
;                 for (int bj = 0; bj < 2; ++bj)
; #pragma unroll
;                     for (int n = 0; n < 2; ++n) { const f32x4 x = acc[ai][bj][m][n]; s += (x[0] + x[1]) + (x[2] + x[3]); }
;                 s += __shfl_xor(s, 16); s += __shfl_xor(s, 32);
;                 const float mw = s * (1.0f / 64.0f); float q = 0.f;
; #pragma unroll
;                 for (int bj = 0; bj < 2; ++bj)
; #pragma unroll
;                     for (int n = 0; n < 2; ++n) { const f32x4 d = acc[ai][bj][m][n] - mw; q += (d[0] * d[0] + d[1] * d[1]) + (d[2] * d[2] + d[3] * d[3]); }
;                 q += __shfl_xor(q, 16); q += __shfl_xor(q, 32);
;                 if (fq == 0) P[(ai * HALF + wr * 64 + m * 16 + fr) * 4 + wc] = (f32x2){mw, q};
.LBB0_1122:
	s_or_b64 exec, exec, s[10:11]
	v_lshlrev_b64 v[134:135], 12, v[132:133]
	v_lshl_add_u64 v[134:135], v[166:167], 0, v[134:135]
	s_waitcnt lgkmcnt(0)
	v_add_co_u32_e32 v138, vcc, 0x80000, v134
	v_lshl_add_u64 v[142:143], v[134:135], 0, s[28:29]
	s_nop 0
	v_addc_co_u32_e32 v139, vcc, 0, v135, vcc
	s_waitcnt vmcnt(7)
	v_mov_b32_e32 v138, v240
	v_mov_b32_e32 v139, v241
	v_mov_b32_e32 v140, v242
	v_mov_b32_e32 v141, v243
	v_lshlrev_b32_e32 v144, 16, v138
	v_and_b32_e32 v145, 0xffff0000, v138
	v_lshlrev_b32_e32 v138, 16, v139
	v_and_b32_e32 v139, 0xffff0000, v139
	v_lshlrev_b32_e32 v146, 16, v140
	v_and_b32_e32 v147, 0xffff0000, v140
	v_lshlrev_b32_e32 v140, 16, v141
	v_and_b32_e32 v141, 0xffff0000, v141
	v_pk_fma_f32 v[130:131], v[138:139], s[92:93], v[130:131] op_sel_hi:[1,0,1]
	v_pk_fma_f32 v[126:127], v[140:141], s[92:93], v[126:127] op_sel_hi:[1,0,1]
	v_pk_fma_f32 v[128:129], v[144:145], s[92:93], v[128:129] op_sel_hi:[1,0,1]
	v_pk_fma_f32 v[124:125], v[146:147], s[92:93], v[124:125] op_sel_hi:[1,0,1]
	s_waitcnt vmcnt(6)
	v_mov_b32_e32 v138, v244
	v_mov_b32_e32 v139, v245
	v_mov_b32_e32 v140, v246
	v_mov_b32_e32 v141, v247
	v_lshlrev_b32_e32 v142, 16, v138
	v_and_b32_e32 v143, 0xffff0000, v138
	v_lshlrev_b32_e32 v138, 16, v139
	v_and_b32_e32 v139, 0xffff0000, v139
	v_lshlrev_b32_e32 v144, 16, v140
	v_and_b32_e32 v145, 0xffff0000, v140
	v_lshlrev_b32_e32 v140, 16, v141
	v_and_b32_e32 v141, 0xffff0000, v141
	v_pk_fma_f32 v[122:123], v[138:139], s[92:93], v[122:123] op_sel_hi:[1,0,1]
	v_pk_fma_f32 v[120:121], v[142:143], s[92:93], v[120:121] op_sel_hi:[1,0,1]
	v_pk_fma_f32 v[118:119], v[140:141], s[92:93], v[118:119] op_sel_hi:[1,0,1]
	v_pk_fma_f32 v[116:117], v[144:145], s[92:93], v[116:117] op_sel_hi:[1,0,1]
	s_nop 0
	s_nop 0
	v_mov_b32_e32 v138, v129
	v_mov_b32_e32 v139, v130
	v_mov_b32_e32 v140, v128
	v_mov_b32_e32 v141, v131
	v_pk_add_f32 v[138:139], v[138:139], v[140:141]
	v_mov_b32_e32 v140, v125
	v_mov_b32_e32 v141, v126
	v_mov_b32_e32 v142, v124
	v_mov_b32_e32 v143, v127
	v_pk_add_f32 v[140:141], v[140:141], v[142:143]
	v_add_f32_e32 v138, v138, v139
	v_pk_add_f32 v[140:141], v[140:141], v[140:141] op_sel_hi:[0,1]
	v_add_f32_e32 v139, 0, v138
	v_add_f32_e32 v143, v120, v121
	v_add_f32_e32 v145, v122, v123
	v_mov_b32_e32 v142, v116
	v_mov_b32_e32 v144, v117
	v_mov_b32_e32 v140, v118
	v_mov_b32_e32 v138, v119
	v_pk_add_f32 v[142:143], v[142:143], v[144:145]
	v_pk_add_f32 v[138:139], v[140:141], v[138:139]
	s_nop 0
	v_pk_add_f32 v[138:139], v[142:143], v[138:139]
	s_nop 0
	v_add_f32_e32 v138, v138, v139
	v_mov_b32_e32 v139, v138
	s_nop 1
	v_permlane16_swap_b32_e32 v139, v138
	s_waitcnt lgkmcnt(0)
	v_add_f32_e32 v138, v138, v139
	v_mov_b32_e32 v139, v138
	s_nop 1
	v_permlane32_swap_b32_e32 v139, v138
	s_waitcnt lgkmcnt(0)
	v_add_f32_e32 v138, v138, v139
	v_fmamk_f32 v140, v138, 0xbc800000, v131
	v_fmamk_f32 v142, v138, 0xbc800000, v129
	v_fmamk_f32 v139, v138, 0xbc800000, v130
	v_fmamk_f32 v141, v138, 0xbc800000, v128
	v_mul_f32_e32 v142, v142, v142
	v_mul_f32_e32 v140, v140, v140
	v_fmac_f32_e32 v142, v141, v141
	v_fmac_f32_e32 v140, v139, v139
	v_fmamk_f32 v141, v138, 0xbc800000, v127
	v_fmamk_f32 v143, v138, 0xbc800000, v125
	v_add_f32_e32 v139, v142, v140
	v_fmamk_f32 v140, v138, 0xbc800000, v126
	v_fmamk_f32 v142, v138, 0xbc800000, v124
	v_mul_f32_e32 v143, v143, v143
	v_mul_f32_e32 v141, v141, v141
	v_fmac_f32_e32 v143, v142, v142
	v_fmac_f32_e32 v141, v140, v140
	v_add_f32_e32 v140, v143, v141
	v_fmamk_f32 v141, v138, 0xbc800000, v123
	v_fmamk_f32 v143, v138, 0xbc800000, v121
	v_add_f32_e32 v139, v139, v140
	v_fmamk_f32 v140, v138, 0xbc800000, v122
	v_fmamk_f32 v142, v138, 0xbc800000, v120
	v_mul_f32_e32 v143, v143, v143
	v_mul_f32_e32 v141, v141, v141
	v_fmac_f32_e32 v143, v142, v142
	v_fmac_f32_e32 v141, v140, v140
	v_add_f32_e32 v140, v143, v141
	v_fmamk_f32 v141, v138, 0xbc800000, v119
	v_fmamk_f32 v143, v138, 0xbc800000, v117
	v_add_f32_e32 v139, v140, v139
	v_fmamk_f32 v140, v138, 0xbc800000, v118
	v_fmamk_f32 v142, v138, 0xbc800000, v116
	v_mul_f32_e32 v143, v143, v143
	v_mul_f32_e32 v141, v141, v141
	v_fmac_f32_e32 v143, v142, v142
	v_fmac_f32_e32 v141, v140, v140
	v_add_f32_e32 v140, v143, v141
	v_add_f32_e32 v139, v140, v139
	v_mov_b32_e32 v140, v139
	s_nop 1
	v_permlane16_swap_b32_e32 v140, v139
	s_waitcnt lgkmcnt(0)
	v_add_f32_e32 v139, v139, v140
	v_mov_b32_e32 v140, v139
	s_nop 1
	v_permlane32_swap_b32_e32 v140, v139
	s_and_saveexec_b64 s[10:11], s[4:5]
	s_cbranch_execz .LBB0_1124
	v_mul_f32_e32 v138, 0x3c800000, v138
	s_waitcnt lgkmcnt(0)
	v_add_f32_e32 v139, v139, v140
	ds_write_b64 v204, v[138:139]
; __device__ __forceinline__ float bflo(unsigned w) { return __uint_as_float(w << 16); }
; __device__ __forceinline__ float bfhi(unsigned w) { return __uint_as_float(w & 0xffff0000u); }
;     __device__ __forceinline__ void operator()(f32x4 (&acc)[2][2][4][2], const Unit& u, int wr, int wc, int fr, int fq, int wid, int lane) const {
;     ...
;             for (int m = 0; m < 4; ++m) { const size_t off = (size_t)(row0 + ai * HALF + m * 16) * D + col0;
; #pragma unroll
;                 for (int bj = 0; bj < 2; ++bj) { f32x4 x0, x1;
;                     if (X) { x0 = *(const f32x4*)(X + off + bj * HALF); x1 = *(const f32x4*)(X + off + bj * HALF + 4); }
;                     else { const u32x4 xw = *(const u32x4*)(XB + off + bj * HALF); x0 = (f32x4){bflo(xw.x), bfhi(xw.x), bflo(xw.y), bfhi(xw.y)}; x1 = (f32x4){bflo(xw.z), bfhi(xw.z), bflo(xw.w), bfhi(xw.w)}; }
;                     acc[ai][bj][m][0] = x0 * ALPHA + acc[ai][bj][m][0]; acc[ai][bj][m][1] = x1 * ALPHA + acc[ai][bj][m][1]; }
;                 asm volatile("" : "+v"(acc[ai][0][m][0]), "+v"(acc[ai][0][m][1]), "+v"(acc[ai][1][m][0]), "+v"(acc[ai][1][m][1]));
;                 float s = 0.f;
; #pragma unroll
;                 for (int bj = 0; bj < 2; ++bj)
; #pragma unroll
;                     for (int n = 0; n < 2; ++n) { const f32x4 x = acc[ai][bj][m][n]; s += (x[0] + x[1]) + (x[2] + x[3]); }
;                 s += __shfl_xor(s, 16); s += __shfl_xor(s, 32);
;                 const float mw = s * (1.0f / 64.0f); float q = 0.f;
; #pragma unroll
;                 for (int bj = 0; bj < 2; ++bj)
; #pragma unroll
;                     for (int n = 0; n < 2; ++n) { const f32x4 d = acc[ai][bj][m][n] - mw; q += (d[0] * d[0] + d[1] * d[1]) + (d[2] * d[2] + d[3] * d[3]); }
;                 q += __shfl_xor(q, 16); q += __shfl_xor(q, 32);
;                 if (fq == 0) P[(ai * HALF + wr * 64 + m * 16 + fr) * 4 + wc] = (f32x2){mw, q};
.LBB0_1124:
	s_or_b64 exec, exec, s[10:11]
	v_lshl_add_u64 v[142:143], v[134:135], 0, s[30:31]
	v_add_co_u32_e32 v134, vcc, 0x90000, v134
	s_nop 1
	v_addc_co_u32_e32 v135, vcc, 0, v135, vcc
	s_waitcnt lgkmcnt(0)
	s_waitcnt vmcnt(5)
	v_mov_b32_e32 v138, v208
	v_mov_b32_e32 v139, v209
	v_mov_b32_e32 v140, v210
	v_mov_b32_e32 v141, v211
	v_lshlrev_b32_e32 v134, 16, v138
	v_and_b32_e32 v135, 0xffff0000, v138
	v_lshlrev_b32_e32 v138, 16, v139
	v_and_b32_e32 v139, 0xffff0000, v139
	v_lshlrev_b32_e32 v144, 16, v140
	v_and_b32_e32 v145, 0xffff0000, v140
	v_lshlrev_b32_e32 v140, 16, v141
	v_and_b32_e32 v141, 0xffff0000, v141
	v_pk_fma_f32 v[106:107], v[138:139], s[92:93], v[106:107] op_sel_hi:[1,0,1]
	v_pk_fma_f32 v[102:103], v[140:141], s[92:93], v[102:103] op_sel_hi:[1,0,1]
	v_pk_fma_f32 v[104:105], v[134:135], s[92:93], v[104:105] op_sel_hi:[1,0,1]
	v_pk_fma_f32 v[100:101], v[144:145], s[92:93], v[100:101] op_sel_hi:[1,0,1]
	s_waitcnt vmcnt(4)
	v_mov_b32_e32 v138, v212
	v_mov_b32_e32 v139, v213
	v_mov_b32_e32 v140, v214
	v_mov_b32_e32 v141, v215
	v_lshlrev_b32_e32 v134, 16, v138
	v_and_b32_e32 v135, 0xffff0000, v138
	v_lshlrev_b32_e32 v138, 16, v139
	v_and_b32_e32 v139, 0xffff0000, v139
	v_lshlrev_b32_e32 v142, 16, v140
	v_and_b32_e32 v143, 0xffff0000, v140
	v_lshlrev_b32_e32 v140, 16, v141
	v_and_b32_e32 v141, 0xffff0000, v141
	v_pk_fma_f32 v[86:87], v[138:139], s[92:93], v[86:87] op_sel_hi:[1,0,1]
	v_pk_fma_f32 v[84:85], v[134:135], s[92:93], v[84:85] op_sel_hi:[1,0,1]
	v_pk_fma_f32 v[82:83], v[140:141], s[92:93], v[82:83] op_sel_hi:[1,0,1]
	v_pk_fma_f32 v[80:81], v[142:143], s[92:93], v[80:81] op_sel_hi:[1,0,1]
	s_nop 0
	s_nop 0
	v_mov_b32_e32 v134, v105
	v_mov_b32_e32 v135, v106
	v_mov_b32_e32 v138, v104
	v_mov_b32_e32 v139, v107
	v_pk_add_f32 v[134:135], v[134:135], v[138:139]
	v_mov_b32_e32 v138, v101
	v_mov_b32_e32 v139, v102
	v_mov_b32_e32 v140, v100
	v_mov_b32_e32 v141, v103
	v_pk_add_f32 v[138:139], v[138:139], v[140:141]
	v_add_f32_e32 v134, v134, v135
	v_pk_add_f32 v[138:139], v[138:139], v[138:139] op_sel_hi:[0,1]
	v_add_f32_e32 v135, 0, v134
	v_add_f32_e32 v141, v84, v85
	v_add_f32_e32 v143, v86, v87
	v_mov_b32_e32 v140, v80
	v_mov_b32_e32 v142, v81
	v_mov_b32_e32 v138, v82
	v_mov_b32_e32 v134, v83
	v_pk_add_f32 v[140:141], v[140:141], v[142:143]
	v_pk_add_f32 v[134:135], v[138:139], v[134:135]
	s_nop 0
	v_pk_add_f32 v[134:135], v[140:141], v[134:135]
	s_nop 0
	v_add_f32_e32 v134, v134, v135
	v_mov_b32_e32 v135, v134
	s_nop 1
	v_permlane16_swap_b32_e32 v135, v134
	s_waitcnt lgkmcnt(0)
	v_add_f32_e32 v134, v134, v135
	v_mov_b32_e32 v135, v134
	s_nop 1
	v_permlane32_swap_b32_e32 v135, v134
	s_waitcnt lgkmcnt(0)
	v_add_f32_e32 v134, v134, v135
	v_fmamk_f32 v138, v134, 0xbc800000, v107
	v_fmamk_f32 v140, v134, 0xbc800000, v105
	v_fmamk_f32 v135, v134, 0xbc800000, v106
	v_fmamk_f32 v139, v134, 0xbc800000, v104
	v_mul_f32_e32 v140, v140, v140
	v_mul_f32_e32 v138, v138, v138
	v_fmac_f32_e32 v140, v139, v139
	v_fmac_f32_e32 v138, v135, v135
	v_fmamk_f32 v139, v134, 0xbc800000, v103
	v_fmamk_f32 v141, v134, 0xbc800000, v101
	v_add_f32_e32 v135, v140, v138
	v_fmamk_f32 v138, v134, 0xbc800000, v102
	v_fmamk_f32 v140, v134, 0xbc800000, v100
	v_mul_f32_e32 v141, v141, v141
	v_mul_f32_e32 v139, v139, v139
	v_fmac_f32_e32 v141, v140, v140
	v_fmac_f32_e32 v139, v138, v138
	v_add_f32_e32 v138, v141, v139
	v_fmamk_f32 v139, v134, 0xbc800000, v87
	v_fmamk_f32 v141, v134, 0xbc800000, v85
	v_add_f32_e32 v135, v135, v138
	v_fmamk_f32 v138, v134, 0xbc800000, v86
	v_fmamk_f32 v140, v134, 0xbc800000, v84
	v_mul_f32_e32 v141, v141, v141
	v_mul_f32_e32 v139, v139, v139
	v_fmac_f32_e32 v141, v140, v140
	v_fmac_f32_e32 v139, v138, v138
	v_add_f32_e32 v138, v141, v139
	v_fmamk_f32 v139, v134, 0xbc800000, v83
	v_fmamk_f32 v141, v134, 0xbc800000, v81
	v_add_f32_e32 v135, v138, v135
	v_fmamk_f32 v138, v134, 0xbc800000, v82
	v_fmamk_f32 v140, v134, 0xbc800000, v80
	v_mul_f32_e32 v141, v141, v141
	v_mul_f32_e32 v139, v139, v139
	v_fmac_f32_e32 v141, v140, v140
	v_fmac_f32_e32 v139, v138, v138
	v_add_f32_e32 v138, v141, v139
	v_add_f32_e32 v135, v138, v135
	v_mov_b32_e32 v138, v135
	s_nop 1
	v_permlane16_swap_b32_e32 v138, v135
	s_waitcnt lgkmcnt(0)
	v_add_f32_e32 v135, v135, v138
	v_mov_b32_e32 v138, v135
	s_nop 1
	v_permlane32_swap_b32_e32 v138, v135
	s_and_saveexec_b64 s[10:11], s[4:5]
	s_cbranch_execz .LBB0_1126
	v_mul_f32_e32 v134, 0x3c800000, v134
	s_waitcnt lgkmcnt(0)
	v_add_f32_e32 v135, v135, v138
	ds_write_b64 v206, v[134:135] offset:4608
; __device__ __forceinline__ float bflo(unsigned w) { return __uint_as_float(w << 16); }
; __device__ __forceinline__ float bfhi(unsigned w) { return __uint_as_float(w & 0xffff0000u); }
;     __device__ __forceinline__ void operator()(f32x4 (&acc)[2][2][4][2], const Unit& u, int wr, int wc, int fr, int fq, int wid, int lane) const {
;     ...
;             for (int m = 0; m < 4; ++m) { const size_t off = (size_t)(row0 + ai * HALF + m * 16) * D + col0;
; #pragma unroll
;                 for (int bj = 0; bj < 2; ++bj) { f32x4 x0, x1;
;                     if (X) { x0 = *(const f32x4*)(X + off + bj * HALF); x1 = *(const f32x4*)(X + off + bj * HALF + 4); }
;                     else { const u32x4 xw = *(const u32x4*)(XB + off + bj * HALF); x0 = (f32x4){bflo(xw.x), bfhi(xw.x), bflo(xw.y), bfhi(xw.y)}; x1 = (f32x4){bflo(xw.z), bfhi(xw.z), bflo(xw.w), bfhi(xw.w)}; }
;                     acc[ai][bj][m][0] = x0 * ALPHA + acc[ai][bj][m][0]; acc[ai][bj][m][1] = x1 * ALPHA + acc[ai][bj][m][1]; }
;                 asm volatile("" : "+v"(acc[ai][0][m][0]), "+v"(acc[ai][0][m][1]), "+v"(acc[ai][1][m][0]), "+v"(acc[ai][1][m][1]));
;                 float s = 0.f;
; #pragma unroll
;                 for (int bj = 0; bj < 2; ++bj)
; #pragma unroll
;                     for (int n = 0; n < 2; ++n) { const f32x4 x = acc[ai][bj][m][n]; s += (x[0] + x[1]) + (x[2] + x[3]); }
;                 s += __shfl_xor(s, 16); s += __shfl_xor(s, 32);
;                 const float mw = s * (1.0f / 64.0f); float q = 0.f;
; #pragma unroll
;                 for (int bj = 0; bj < 2; ++bj)
; #pragma unroll
;                     for (int n = 0; n < 2; ++n) { const f32x4 d = acc[ai][bj][m][n] - mw; q += (d[0] * d[0] + d[1] * d[1]) + (d[2] * d[2] + d[3] * d[3]); }
;                 q += __shfl_xor(q, 16); q += __shfl_xor(q, 32);
;                 if (fq == 0) P[(ai * HALF + wr * 64 + m * 16 + fr) * 4 + wc] = (f32x2){mw, q};
.LBB0_1126:
	s_or_b64 exec, exec, s[10:11]
	v_lshlrev_b64 v[132:133], 12, v[132:133]
	v_lshl_add_u64 v[132:133], v[166:167], 0, v[132:133]
	s_waitcnt lgkmcnt(0)
	v_add_co_u32_e32 v138, vcc, 0xa0000, v132
	v_lshl_add_u64 v[134:135], v[132:133], 0, s[36:37]
	s_nop 0
	v_addc_co_u32_e32 v139, vcc, 0, v133, vcc
	s_waitcnt vmcnt(3)
	v_mov_b32_e32 v138, v216
	v_mov_b32_e32 v139, v217
	v_mov_b32_e32 v140, v218
	v_mov_b32_e32 v141, v219
	v_lshlrev_b32_e32 v142, 16, v138
	v_and_b32_e32 v143, 0xffff0000, v138
	v_lshlrev_b32_e32 v138, 16, v139
	v_and_b32_e32 v139, 0xffff0000, v139
	v_lshlrev_b32_e32 v144, 16, v140
	v_and_b32_e32 v145, 0xffff0000, v140
	v_lshlrev_b32_e32 v140, 16, v141
	v_and_b32_e32 v141, 0xffff0000, v141
	v_pk_fma_f32 v[74:75], v[138:139], s[92:93], v[74:75] op_sel_hi:[1,0,1]
	v_pk_fma_f32 v[70:71], v[140:141], s[92:93], v[70:71] op_sel_hi:[1,0,1]
	v_pk_fma_f32 v[72:73], v[142:143], s[92:93], v[72:73] op_sel_hi:[1,0,1]
	v_pk_fma_f32 v[68:69], v[144:145], s[92:93], v[68:69] op_sel_hi:[1,0,1]
	s_waitcnt vmcnt(2)
	v_mov_b32_e32 v138, v220
	v_mov_b32_e32 v139, v221
	v_mov_b32_e32 v140, v222
	v_mov_b32_e32 v141, v223
	v_lshlrev_b32_e32 v134, 16, v138
	v_and_b32_e32 v135, 0xffff0000, v138
	v_lshlrev_b32_e32 v138, 16, v139
	v_and_b32_e32 v139, 0xffff0000, v139
	v_lshlrev_b32_e32 v142, 16, v140
	v_and_b32_e32 v143, 0xffff0000, v140
	v_lshlrev_b32_e32 v140, 16, v141
	v_and_b32_e32 v141, 0xffff0000, v141
	v_pk_fma_f32 v[50:51], v[138:139], s[92:93], v[50:51] op_sel_hi:[1,0,1]
	v_pk_fma_f32 v[48:49], v[134:135], s[92:93], v[48:49] op_sel_hi:[1,0,1]
	v_pk_fma_f32 v[46:47], v[140:141], s[92:93], v[46:47] op_sel_hi:[1,0,1]
	v_pk_fma_f32 v[44:45], v[142:143], s[92:93], v[44:45] op_sel_hi:[1,0,1]
	s_nop 0
	s_nop 0
	v_mov_b32_e32 v134, v73
	v_mov_b32_e32 v135, v74
	v_mov_b32_e32 v138, v72
	v_mov_b32_e32 v139, v75
	v_pk_add_f32 v[134:135], v[134:135], v[138:139]
	v_mov_b32_e32 v138, v69
	v_mov_b32_e32 v139, v70
	v_mov_b32_e32 v140, v68
	v_mov_b32_e32 v141, v71
	v_pk_add_f32 v[138:139], v[138:139], v[140:141]
	v_add_f32_e32 v134, v134, v135
	v_pk_add_f32 v[138:139], v[138:139], v[138:139] op_sel_hi:[0,1]
	v_add_f32_e32 v135, 0, v134
	v_add_f32_e32 v141, v48, v49
	v_add_f32_e32 v143, v50, v51
	v_mov_b32_e32 v140, v44
	v_mov_b32_e32 v142, v45
	v_mov_b32_e32 v138, v46
	v_mov_b32_e32 v134, v47
	v_pk_add_f32 v[140:141], v[140:141], v[142:143]
	v_pk_add_f32 v[134:135], v[138:139], v[134:135]
	s_nop 0
	v_pk_add_f32 v[134:135], v[140:141], v[134:135]
	s_nop 0
	v_add_f32_e32 v134, v134, v135
	v_mov_b32_e32 v135, v134
	s_nop 1
	v_permlane16_swap_b32_e32 v135, v134
	s_waitcnt lgkmcnt(0)
	v_add_f32_e32 v134, v134, v135
	v_mov_b32_e32 v135, v134
	s_nop 1
	v_permlane32_swap_b32_e32 v135, v134
	s_waitcnt lgkmcnt(0)
	v_add_f32_e32 v134, v134, v135
	v_fmamk_f32 v138, v134, 0xbc800000, v75
	v_fmamk_f32 v140, v134, 0xbc800000, v73
	v_fmamk_f32 v135, v134, 0xbc800000, v74
	v_fmamk_f32 v139, v134, 0xbc800000, v72
	v_mul_f32_e32 v140, v140, v140
	v_mul_f32_e32 v138, v138, v138
	v_fmac_f32_e32 v140, v139, v139
	v_fmac_f32_e32 v138, v135, v135
	v_fmamk_f32 v139, v134, 0xbc800000, v71
	v_fmamk_f32 v141, v134, 0xbc800000, v69
	v_add_f32_e32 v135, v140, v138
	v_fmamk_f32 v138, v134, 0xbc800000, v70
	v_fmamk_f32 v140, v134, 0xbc800000, v68
	v_mul_f32_e32 v141, v141, v141
	v_mul_f32_e32 v139, v139, v139
	v_fmac_f32_e32 v141, v140, v140
	v_fmac_f32_e32 v139, v138, v138
	v_add_f32_e32 v138, v141, v139
	v_fmamk_f32 v139, v134, 0xbc800000, v51
	v_fmamk_f32 v141, v134, 0xbc800000, v49
	v_add_f32_e32 v135, v135, v138
	v_fmamk_f32 v138, v134, 0xbc800000, v50
	v_fmamk_f32 v140, v134, 0xbc800000, v48
	v_mul_f32_e32 v141, v141, v141
	v_mul_f32_e32 v139, v139, v139
	v_fmac_f32_e32 v141, v140, v140
	v_fmac_f32_e32 v139, v138, v138
	v_add_f32_e32 v138, v141, v139
	v_fmamk_f32 v139, v134, 0xbc800000, v47
	v_fmamk_f32 v141, v134, 0xbc800000, v45
	v_add_f32_e32 v135, v138, v135
	v_fmamk_f32 v138, v134, 0xbc800000, v46
	v_fmamk_f32 v140, v134, 0xbc800000, v44
	v_mul_f32_e32 v141, v141, v141
	v_mul_f32_e32 v139, v139, v139
	v_fmac_f32_e32 v141, v140, v140
	v_fmac_f32_e32 v139, v138, v138
	v_add_f32_e32 v138, v141, v139
	v_add_f32_e32 v135, v138, v135
	v_mov_b32_e32 v138, v135
	s_nop 1
	v_permlane16_swap_b32_e32 v138, v135
	s_waitcnt lgkmcnt(0)
	v_add_f32_e32 v135, v135, v138
	v_mov_b32_e32 v138, v135
	s_nop 1
	v_permlane32_swap_b32_e32 v138, v135
	s_and_saveexec_b64 s[10:11], s[4:5]
	s_cbranch_execz .LBB0_1128
	v_mul_f32_e32 v134, 0x3c800000, v134
	s_waitcnt lgkmcnt(0)
	v_add_f32_e32 v135, v135, v138
	ds_write_b64 v206, v[134:135] offset:5120
; __device__ __forceinline__ float bflo(unsigned w) { return __uint_as_float(w << 16); }
; __device__ __forceinline__ float bfhi(unsigned w) { return __uint_as_float(w & 0xffff0000u); }
;     __device__ __forceinline__ void operator()(f32x4 (&acc)[2][2][4][2], const Unit& u, int wr, int wc, int fr, int fq, int wid, int lane) const {
;     ...
;             for (int m = 0; m < 4; ++m) { const size_t off = (size_t)(row0 + ai * HALF + m * 16) * D + col0;
; #pragma unroll
;                 for (int bj = 0; bj < 2; ++bj) { f32x4 x0, x1;
;                     if (X) { x0 = *(const f32x4*)(X + off + bj * HALF); x1 = *(const f32x4*)(X + off + bj * HALF + 4); }
;                     else { const u32x4 xw = *(const u32x4*)(XB + off + bj * HALF); x0 = (f32x4){bflo(xw.x), bfhi(xw.x), bflo(xw.y), bfhi(xw.y)}; x1 = (f32x4){bflo(xw.z), bfhi(xw.z), bflo(xw.w), bfhi(xw.w)}; }
;                     acc[ai][bj][m][0] = x0 * ALPHA + acc[ai][bj][m][0]; acc[ai][bj][m][1] = x1 * ALPHA + acc[ai][bj][m][1]; }
;                 asm volatile("" : "+v"(acc[ai][0][m][0]), "+v"(acc[ai][0][m][1]), "+v"(acc[ai][1][m][0]), "+v"(acc[ai][1][m][1]));
;                 float s = 0.f;
; #pragma unroll
;                 for (int bj = 0; bj < 2; ++bj)
; #pragma unroll
;                     for (int n = 0; n < 2; ++n) { const f32x4 x = acc[ai][bj][m][n]; s += (x[0] + x[1]) + (x[2] + x[3]); }
;                 s += __shfl_xor(s, 16); s += __shfl_xor(s, 32);
;                 const float mw = s * (1.0f / 64.0f); float q = 0.f;
; #pragma unroll
;                 for (int bj = 0; bj < 2; ++bj)
; #pragma unroll
;                     for (int n = 0; n < 2; ++n) { const f32x4 d = acc[ai][bj][m][n] - mw; q += (d[0] * d[0] + d[1] * d[1]) + (d[2] * d[2] + d[3] * d[3]); }
;                 q += __shfl_xor(q, 16); q += __shfl_xor(q, 32);
;                 if (fq == 0) P[(ai * HALF + wr * 64 + m * 16 + fr) * 4 + wc] = (f32x2){mw, q};
.LBB0_1128:
	s_or_b64 exec, exec, s[10:11]
	s_mov_b64 s[10:11], 0xb0000
	s_waitcnt lgkmcnt(0)
	v_lshl_add_u64 v[138:139], v[132:133], 0, s[10:11]
	v_add_co_u32_e32 v132, vcc, 0xb0000, v132
	s_nop 1
	v_addc_co_u32_e32 v133, vcc, 0, v133, vcc
	s_waitcnt vmcnt(1)
	v_mov_b32_e32 v132, v224
	v_mov_b32_e32 v133, v225
	v_mov_b32_e32 v134, v226
	v_mov_b32_e32 v135, v227
	v_lshlrev_b32_e32 v140, 16, v132
	v_and_b32_e32 v141, 0xffff0000, v132
	v_lshlrev_b32_e32 v132, 16, v133
	v_and_b32_e32 v133, 0xffff0000, v133
	v_lshlrev_b32_e32 v142, 16, v134
	v_and_b32_e32 v143, 0xffff0000, v134
	v_lshlrev_b32_e32 v134, 16, v135
	v_and_b32_e32 v135, 0xffff0000, v135
	v_pk_fma_f32 v[34:35], v[132:133], s[92:93], v[34:35] op_sel_hi:[1,0,1]
	v_pk_fma_f32 v[30:31], v[134:135], s[92:93], v[30:31] op_sel_hi:[1,0,1]
	v_pk_fma_f32 v[32:33], v[140:141], s[92:93], v[32:33] op_sel_hi:[1,0,1]
	v_pk_fma_f32 v[28:29], v[142:143], s[92:93], v[28:29] op_sel_hi:[1,0,1]
	s_waitcnt vmcnt(0)
	v_mov_b32_e32 v132, v228
	v_mov_b32_e32 v133, v229
	v_mov_b32_e32 v134, v230
	v_mov_b32_e32 v135, v231
	v_lshlrev_b32_e32 v138, 16, v132
	v_and_b32_e32 v139, 0xffff0000, v132
	v_lshlrev_b32_e32 v132, 16, v133
	v_and_b32_e32 v133, 0xffff0000, v133
	v_lshlrev_b32_e32 v140, 16, v134
	v_and_b32_e32 v141, 0xffff0000, v134
	v_lshlrev_b32_e32 v134, 16, v135
	v_and_b32_e32 v135, 0xffff0000, v135
	v_pk_fma_f32 v[26:27], v[132:133], s[92:93], v[26:27] op_sel_hi:[1,0,1]
	v_pk_fma_f32 v[24:25], v[138:139], s[92:93], v[24:25] op_sel_hi:[1,0,1]
	v_pk_fma_f32 v[22:23], v[134:135], s[92:93], v[22:23] op_sel_hi:[1,0,1]
	v_pk_fma_f32 v[20:21], v[140:141], s[92:93], v[20:21] op_sel_hi:[1,0,1]
	s_nop 0
	s_nop 0
	v_mov_b32_e32 v132, v33
	v_mov_b32_e32 v133, v34
	v_mov_b32_e32 v134, v32
	v_mov_b32_e32 v135, v35
	v_pk_add_f32 v[132:133], v[132:133], v[134:135]
	v_mov_b32_e32 v134, v29
	v_mov_b32_e32 v135, v30
	v_mov_b32_e32 v138, v28
	v_mov_b32_e32 v139, v31
	v_pk_add_f32 v[134:135], v[134:135], v[138:139]
	v_add_f32_e32 v132, v132, v133
	v_pk_add_f32 v[134:135], v[134:135], v[134:135] op_sel_hi:[0,1]
	v_add_f32_e32 v133, 0, v132
	v_add_f32_e32 v139, v24, v25
	v_add_f32_e32 v141, v26, v27
	v_mov_b32_e32 v138, v20
	v_mov_b32_e32 v140, v21
	v_mov_b32_e32 v134, v22
	v_mov_b32_e32 v132, v23
	v_pk_add_f32 v[138:139], v[138:139], v[140:141]
	v_pk_add_f32 v[132:133], v[134:135], v[132:133]
	s_nop 0
	v_pk_add_f32 v[132:133], v[138:139], v[132:133]
	s_nop 0
	v_add_f32_e32 v132, v132, v133
	v_mov_b32_e32 v133, v132
	s_nop 1
	v_permlane16_swap_b32_e32 v133, v132
	s_waitcnt lgkmcnt(0)
	v_add_f32_e32 v132, v132, v133
	v_mov_b32_e32 v133, v132
	s_nop 1
	v_permlane32_swap_b32_e32 v133, v132
	s_waitcnt lgkmcnt(0)
	v_add_f32_e32 v132, v132, v133
	v_fmamk_f32 v134, v132, 0xbc800000, v35
	v_fmamk_f32 v138, v132, 0xbc800000, v33
	v_fmamk_f32 v133, v132, 0xbc800000, v34
	v_fmamk_f32 v135, v132, 0xbc800000, v32
	v_mul_f32_e32 v138, v138, v138
	v_mul_f32_e32 v134, v134, v134
	v_fmac_f32_e32 v138, v135, v135
	v_fmac_f32_e32 v134, v133, v133
	v_fmamk_f32 v135, v132, 0xbc800000, v31
	v_fmamk_f32 v139, v132, 0xbc800000, v29
	v_add_f32_e32 v133, v138, v134
	v_fmamk_f32 v134, v132, 0xbc800000, v30
	v_fmamk_f32 v138, v132, 0xbc800000, v28
	v_mul_f32_e32 v139, v139, v139
	v_mul_f32_e32 v135, v135, v135
	v_fmac_f32_e32 v139, v138, v138
	v_fmac_f32_e32 v135, v134, v134
	v_add_f32_e32 v134, v139, v135
	v_fmamk_f32 v135, v132, 0xbc800000, v27
	v_fmamk_f32 v139, v132, 0xbc800000, v25
	v_add_f32_e32 v133, v133, v134
	v_fmamk_f32 v134, v132, 0xbc800000, v26
	v_fmamk_f32 v138, v132, 0xbc800000, v24
	v_mul_f32_e32 v139, v139, v139
	v_mul_f32_e32 v135, v135, v135
	v_fmac_f32_e32 v139, v138, v138
	v_fmac_f32_e32 v135, v134, v134
	v_add_f32_e32 v134, v139, v135
	v_fmamk_f32 v135, v132, 0xbc800000, v23
	v_fmamk_f32 v139, v132, 0xbc800000, v21
	v_add_f32_e32 v133, v134, v133
	v_fmamk_f32 v134, v132, 0xbc800000, v22
	v_fmamk_f32 v138, v132, 0xbc800000, v20
	v_mul_f32_e32 v139, v139, v139
	v_mul_f32_e32 v135, v135, v135
	v_fmac_f32_e32 v139, v138, v138
	v_fmac_f32_e32 v135, v134, v134
	v_add_f32_e32 v134, v139, v135
	v_add_f32_e32 v133, v134, v133
	v_mov_b32_e32 v134, v133
	s_nop 1
	v_permlane16_swap_b32_e32 v134, v133
	s_waitcnt lgkmcnt(0)
	v_add_f32_e32 v133, v133, v134
	v_mov_b32_e32 v134, v133
	s_nop 1
	v_permlane32_swap_b32_e32 v134, v133
	s_and_saveexec_b64 s[10:11], s[4:5]
	s_cbranch_execz .LBB0_1130
	v_mul_f32_e32 v132, 0x3c800000, v132
	s_waitcnt lgkmcnt(0)
	v_add_f32_e32 v133, v133, v134
	ds_write_b64 v206, v[132:133] offset:5632
